# p12 + O1 epilogue: same ds_bpermute lane transpose of the bf16 output chunks
# baseline (speedup 1.0000x reference)
.LBB0_171:
.LBB0_173:
	v_mbcnt_lo_u32_b32 v255, -1, 0
	v_mbcnt_hi_u32_b32 v255, -1, v255
	v_lshrrev_b32_e32 v250, 2, v255
	v_and_b32_e32 v251, 3, v255
	v_and_b32_e32 v252, 15, v255
	v_lshrrev_b32_e32 v253, 4, v255
	v_sub_u32_e32 v252, v250, v252
	v_sub_u32_e32 v253, v251, v253
	v_mul_i32_i24_e32 v252, 0x2000, v252
	v_lshl_add_u32 v208, v253, 4, v252
	v_ashrrev_i32_e32 v209, 31, v208
	v_lshl_add_u32 v255, v251, 4, v250
	v_lshlrev_b32_e32 v255, 2, v255
	ds_read_b128 v[152:155], v167
	v_add_u32_e32 v150, s0, v156
	s_cmp_gt_i32 s12, 7
	s_cselect_b64 s[0:1], -1, 0
	s_and_b64 s[2:3], s[6:7], s[0:1]
	s_waitcnt lgkmcnt(0)
	v_lshlrev_b32_e32 v0, 16, v152
	v_and_b32_e32 v151, 0xffff0000, v152
	v_add_f32_e32 v0, v0, v151
	v_lshlrev_b32_e32 v151, 16, v153
	v_and_b32_e32 v152, 0xffff0000, v153
	v_add_f32_e32 v151, v151, v152
	v_add_f32_e32 v0, v0, v151
	v_lshlrev_b32_e32 v151, 16, v154
	v_and_b32_e32 v152, 0xffff0000, v154
	v_add_f32_e32 v151, v151, v152
	v_lshlrev_b32_e32 v152, 16, v155
	v_and_b32_e32 v153, 0xffff0000, v155
	v_add_f32_e32 v152, v152, v153
	v_add_f32_e32 v151, v151, v152
	v_add_f32_e32 v0, v0, v151
	v_mov_b32_e32 v151, v0
	s_nop 1
	v_permlane16_swap_b32_e32 v0, v151
	v_add_f32_e32 v0, v0, v151
	ds_read_b128 v[152:155], v167 offset:1024
	v_mov_b32_e32 v151, v0
	s_nop 1
	v_permlane32_swap_b32_e32 v0, v151
	v_add_f32_e32 v0, v0, v151
	v_fmamk_f32 v0, v0, 0x3a000000, v240
	v_rsq_f32_e32 v0, v0
	s_waitcnt lgkmcnt(0)
	v_lshlrev_b32_e32 v151, 16, v152
	v_and_b32_e32 v152, 0xffff0000, v152
	v_add_f32_e32 v151, v151, v152
	v_lshlrev_b32_e32 v152, 16, v153
	v_and_b32_e32 v153, 0xffff0000, v153
	v_add_f32_e32 v152, v152, v153
	v_add_f32_e32 v151, v151, v152
	v_lshlrev_b32_e32 v152, 16, v154
	v_and_b32_e32 v153, 0xffff0000, v154
	v_add_f32_e32 v152, v152, v153
	v_lshlrev_b32_e32 v153, 16, v155
	v_and_b32_e32 v154, 0xffff0000, v155
	s_mov_b64 vcc, s[14:15]
	s_cbranch_vccz .Lalign_skip_0
	s_barrier
.Lalign_skip_0:
	v_pk_mul_f32 v[122:123], v[122:123], v[0:1] op_sel_hi:[1,0]
	v_add_f32_e32 v153, v153, v154
	v_mul_f32_e32 v178, 0x3d372713, v122
	v_add_f32_e32 v152, v152, v153
	v_mul_f32_e32 v177, 0x3fcc422a, v122
	v_fma_f32 v178, v122, v178, 1.0
	v_add_f32_e32 v151, v151, v152
	v_mul_f32_e32 v177, v177, v178
	v_mov_b32_e32 v152, v151
	v_mul_f32_e32 v177, 0xbfb8aa3b, v177
	s_nop 0
	v_permlane16_swap_b32_e32 v151, v152
	v_exp_f32_e32 v177, v177
	v_add_f32_e32 v175, v151, v152
	ds_read_b128 v[152:155], v167 offset:2048
	v_mul_f32_e32 v178, 0x3d372713, v123
	v_add_f32_e32 v177, 1.0, v177
	v_rcp_f32_e32 v177, v177
	v_fma_f32 v178, v123, v178, 1.0
	s_waitcnt lgkmcnt(0)
	v_lshlrev_b32_e32 v151, 16, v152
	v_and_b32_e32 v152, 0xffff0000, v152
	v_add_f32_e32 v151, v151, v152
	v_lshlrev_b32_e32 v152, 16, v153
	v_and_b32_e32 v153, 0xffff0000, v153
	v_add_f32_e32 v152, v152, v153
	v_add_f32_e32 v151, v151, v152
	v_lshlrev_b32_e32 v152, 16, v154
	v_and_b32_e32 v153, 0xffff0000, v154
	v_mul_f32_e32 v122, v122, v177
	v_mul_f32_e32 v177, 0x3fcc422a, v123
	v_add_f32_e32 v152, v152, v153
	v_lshlrev_b32_e32 v153, 16, v155
	v_and_b32_e32 v154, 0xffff0000, v155
	v_mul_f32_e32 v177, v177, v178
	v_add_f32_e32 v153, v153, v154
	v_mul_f32_e32 v177, 0xbfb8aa3b, v177
	v_add_f32_e32 v152, v152, v153
	v_exp_f32_e32 v177, v177
	v_add_f32_e32 v151, v151, v152
	v_mov_b32_e32 v152, v151
	s_nop 1
	v_permlane16_swap_b32_e32 v151, v152
	v_add_f32_e32 v173, v151, v152
	ds_read_b128 v[152:155], v167 offset:3072
	v_add_f32_e32 v177, 1.0, v177
	v_rcp_f32_e32 v177, v177
	v_pk_mul_f32 v[124:125], v[124:125], v[0:1] op_sel_hi:[1,0]
	v_pk_mul_f32 v[126:127], v[126:127], v[0:1] op_sel_hi:[1,0]
	v_mul_f32_e32 v178, 0x3d372713, v124
	s_waitcnt lgkmcnt(0)
	v_lshlrev_b32_e32 v151, 16, v152
	v_and_b32_e32 v152, 0xffff0000, v152
	v_mul_f32_e32 v123, v123, v177
	v_mul_f32_e32 v177, 0x3fcc422a, v124
	v_fma_f32 v178, v124, v178, 1.0
	v_add_f32_e32 v151, v151, v152
	v_lshlrev_b32_e32 v152, 16, v153
	v_and_b32_e32 v153, 0xffff0000, v153
	v_mul_f32_e32 v177, v177, v178
	v_add_f32_e32 v152, v152, v153
	v_mul_f32_e32 v177, 0xbfb8aa3b, v177
	v_add_f32_e32 v151, v151, v152
	v_lshlrev_b32_e32 v152, 16, v154
	v_and_b32_e32 v153, 0xffff0000, v154
	v_exp_f32_e32 v177, v177
	v_add_f32_e32 v152, v152, v153
	v_lshlrev_b32_e32 v153, 16, v155
	v_and_b32_e32 v154, 0xffff0000, v155
	v_add_f32_e32 v153, v153, v154
	v_add_f32_e32 v152, v152, v153
	v_add_f32_e32 v151, v151, v152
	v_add_f32_e32 v177, 1.0, v177
	v_mov_b32_e32 v152, v151
	v_rcp_f32_e32 v177, v177
	s_nop 0
	v_permlane16_swap_b32_e32 v151, v152
	v_add_f32_e32 v171, v151, v152
	ds_read_b128 v[152:155], v167 offset:8192
	v_mul_f32_e32 v178, 0x3d372713, v125
	v_mul_f32_e32 v124, v124, v177
	v_mul_f32_e32 v177, 0x3fcc422a, v125
	v_fma_f32 v178, v125, v178, 1.0
	v_mul_f32_e32 v177, v177, v178
	v_mul_f32_e32 v177, 0xbfb8aa3b, v177
	s_waitcnt lgkmcnt(0)
	v_lshlrev_b32_e32 v151, 16, v152
	v_and_b32_e32 v152, 0xffff0000, v152
	v_exp_f32_e32 v177, v177
	v_add_f32_e32 v151, v151, v152
	v_lshlrev_b32_e32 v152, 16, v153
	v_and_b32_e32 v153, 0xffff0000, v153
	v_add_f32_e32 v152, v152, v153
	v_add_f32_e32 v151, v151, v152
	v_lshlrev_b32_e32 v152, 16, v154
	v_and_b32_e32 v153, 0xffff0000, v154
	v_add_f32_e32 v152, v152, v153
	v_lshlrev_b32_e32 v153, 16, v155
	v_and_b32_e32 v154, 0xffff0000, v155
	v_add_f32_e32 v177, 1.0, v177
	v_add_f32_e32 v153, v153, v154
	v_rcp_f32_e32 v177, v177
	v_add_f32_e32 v152, v152, v153
	v_add_f32_e32 v151, v151, v152
	v_mov_b32_e32 v152, v151
	v_mul_f32_e32 v178, 0x3d372713, v126
	s_nop 0
	v_permlane16_swap_b32_e32 v151, v152
	v_mul_f32_e32 v125, v125, v177
	v_mul_f32_e32 v177, 0x3fcc422a, v126
	v_fma_f32 v178, v126, v178, 1.0
	v_add_f32_e32 v169, v151, v152
	ds_read_b128 v[152:155], v167 offset:9216
	v_mul_f32_e32 v177, v177, v178
	v_mul_f32_e32 v177, 0xbfb8aa3b, v177
	v_exp_f32_e32 v177, v177
	v_mul_f32_e32 v178, 0x3d372713, v127
	s_waitcnt lgkmcnt(0)
	v_lshlrev_b32_e32 v151, 16, v152
	v_and_b32_e32 v152, 0xffff0000, v152
	v_add_f32_e32 v151, v151, v152
	v_lshlrev_b32_e32 v152, 16, v153
	v_and_b32_e32 v153, 0xffff0000, v153
	v_add_f32_e32 v177, 1.0, v177
	v_add_f32_e32 v152, v152, v153
	v_rcp_f32_e32 v177, v177
	v_add_f32_e32 v151, v151, v152
	v_lshlrev_b32_e32 v152, 16, v154
	v_and_b32_e32 v153, 0xffff0000, v154
	v_add_f32_e32 v152, v152, v153
	v_lshlrev_b32_e32 v153, 16, v155
	v_and_b32_e32 v154, 0xffff0000, v155
	v_add_f32_e32 v153, v153, v154
	v_add_f32_e32 v152, v152, v153
	v_mul_f32_e32 v126, v126, v177
	v_mul_f32_e32 v177, 0x3fcc422a, v127
	v_fma_f32 v178, v127, v178, 1.0
	v_add_f32_e32 v151, v151, v152
	v_mul_f32_e32 v177, v177, v178
	v_mov_b32_e32 v152, v151
	v_mul_f32_e32 v177, 0xbfb8aa3b, v177
	s_nop 0
	v_permlane16_swap_b32_e32 v151, v152
	v_exp_f32_e32 v177, v177
	v_add_f32_e32 v161, v151, v152
	ds_read_b128 v[152:155], v167 offset:10240
	v_pk_mul_f32 v[128:129], v[128:129], v[0:1] op_sel_hi:[1,0]
	v_add_f32_e32 v177, 1.0, v177
	v_rcp_f32_e32 v177, v177
	v_mul_f32_e32 v178, 0x3d372713, v128
	s_waitcnt lgkmcnt(0)
	v_lshlrev_b32_e32 v151, 16, v152
	v_and_b32_e32 v152, 0xffff0000, v152
	v_add_f32_e32 v151, v151, v152
	v_lshlrev_b32_e32 v152, 16, v153
	v_and_b32_e32 v153, 0xffff0000, v153
	v_add_f32_e32 v152, v152, v153
	v_add_f32_e32 v151, v151, v152
	v_lshlrev_b32_e32 v152, 16, v154
	v_and_b32_e32 v153, 0xffff0000, v154
	v_mul_f32_e32 v127, v127, v177
	v_mul_f32_e32 v177, 0x3fcc422a, v128
	v_fma_f32 v178, v128, v178, 1.0
	v_add_f32_e32 v152, v152, v153
	v_lshlrev_b32_e32 v153, 16, v155
	v_and_b32_e32 v154, 0xffff0000, v155
	v_mul_f32_e32 v177, v177, v178
	v_add_f32_e32 v153, v153, v154
	v_mul_f32_e32 v177, 0xbfb8aa3b, v177
	v_add_f32_e32 v152, v152, v153
	v_exp_f32_e32 v177, v177
	v_add_f32_e32 v151, v151, v152
	v_mov_b32_e32 v152, v151
	s_nop 1
	v_permlane16_swap_b32_e32 v151, v152
	v_add_f32_e32 v159, v151, v152
	ds_read_b128 v[152:155], v167 offset:11264
	v_add_f32_e32 v177, 1.0, v177
	v_rcp_f32_e32 v177, v177
	v_mul_f32_e32 v178, 0x3d372713, v129
	v_fma_f32 v178, v129, v178, 1.0
	s_waitcnt lgkmcnt(0)
	v_lshlrev_b32_e32 v151, 16, v152
	v_and_b32_e32 v152, 0xffff0000, v152
	v_mul_f32_e32 v128, v128, v177
	v_mul_f32_e32 v177, 0x3fcc422a, v129
	v_add_f32_e32 v151, v151, v152
	v_lshlrev_b32_e32 v152, 16, v153
	v_and_b32_e32 v153, 0xffff0000, v153
	v_mul_f32_e32 v177, v177, v178
	v_add_f32_e32 v152, v152, v153
	v_mul_f32_e32 v177, 0xbfb8aa3b, v177
	v_add_f32_e32 v151, v151, v152
	v_lshlrev_b32_e32 v152, 16, v154
	v_and_b32_e32 v153, 0xffff0000, v154
	v_exp_f32_e32 v177, v177
	v_add_f32_e32 v152, v152, v153
	v_lshlrev_b32_e32 v153, 16, v155
	v_and_b32_e32 v154, 0xffff0000, v155
	v_add_f32_e32 v153, v153, v154
	v_add_f32_e32 v152, v152, v153
	v_add_f32_e32 v151, v151, v152
	v_add_f32_e32 v177, 1.0, v177
	v_mov_b32_e32 v152, v151
	v_rcp_f32_e32 v177, v177
	s_nop 0
	v_permlane16_swap_b32_e32 v151, v152
	v_add_f32_e32 v157, v151, v152
	v_lshl_or_b32 v152, s12, 8, v165
	v_ashrrev_i32_e32 v153, 31, v152
	v_ashrrev_i32_e32 v151, 31, v150
	v_lshl_add_u64 v[152:153], v[152:153], 1, v[140:141]
	v_lshlrev_b64 v[154:155], 13, v[150:151]
	v_mul_f32_e32 v129, v129, v177
	v_mul_f32_e32 v177, v123, v123
	v_lshl_add_u64 v[154:155], v[152:153], 0, v[154:155]
	v_fmac_f32_e32 v177, v122, v122
	v_mul_f32_e32 v178, v125, v125
	v_cvt_pk_bf16_f32 v122, v122, v123
	v_pk_mul_f32 v[114:115], v[114:115], v[0:1] op_sel_hi:[1,0]
	v_fmac_f32_e32 v178, v124, v124
	v_cvt_pk_bf16_f32 v123, v124, v125
	v_cvt_pk_bf16_f32 v124, v126, v127
	v_cvt_pk_bf16_f32 v125, v128, v129
	ds_bpermute_b32 v250, v255, v122
	ds_bpermute_b32 v251, v255, v123
	ds_bpermute_b32 v252, v255, v124
	ds_bpermute_b32 v253, v255, v125
	v_pk_mul_f32 v[116:117], v[116:117], v[0:1] op_sel_hi:[1,0]
	v_pk_mul_f32 v[120:121], v[120:121], v[0:1] op_sel_hi:[1,0]
	v_mul_f32_e32 v122, 0x3d372713, v114
	v_pk_mul_f32 v[118:119], v[118:119], v[0:1] op_sel_hi:[1,0]
	v_mul_f32_e32 v0, 0x3fcc422a, v114
	v_fma_f32 v122, v114, v122, 1.0
	v_mul_f32_e32 v0, v0, v122
	v_mul_f32_e32 v0, 0xbfb8aa3b, v0
	v_exp_f32_e32 v0, v0
	v_mul_f32_e32 v122, 0x3d372713, v115
	v_fma_f32 v122, v115, v122, 1.0
	v_add_f32_e32 v177, v177, v178
	v_add_f32_e32 v0, 1.0, v0
	v_rcp_f32_e32 v0, v0
	v_mul_f32_e32 v178, v127, v127
	v_mul_f32_e32 v179, v129, v129
	v_fmac_f32_e32 v178, v126, v126
	v_mul_f32_e32 v0, v114, v0
	v_mul_f32_e32 v114, 0x3fcc422a, v115
	v_mul_f32_e32 v114, v114, v122
	v_mul_f32_e32 v114, 0xbfb8aa3b, v114
	v_exp_f32_e32 v114, v114
	v_mul_f32_e32 v122, 0x3d372713, v116
	v_fma_f32 v122, v116, v122, 1.0
	v_fmac_f32_e32 v179, v128, v128
	v_add_f32_e32 v114, 1.0, v114
	v_rcp_f32_e32 v114, v114
	v_add_f32_e32 v178, v178, v179
	v_add_f32_e32 v177, v177, v178
	v_mov_b32_e32 v176, v175
	v_mul_f32_e32 v114, v115, v114
	v_mul_f32_e32 v115, 0x3fcc422a, v116
	v_mul_f32_e32 v115, v115, v122
	v_mul_f32_e32 v115, 0xbfb8aa3b, v115
	v_exp_f32_e32 v115, v115
	v_mul_f32_e32 v122, 0x3d372713, v117
	v_fma_f32 v122, v117, v122, 1.0
	v_mov_b32_e32 v174, v173
	v_add_f32_e32 v115, 1.0, v115
	v_rcp_f32_e32 v115, v115
	v_mov_b32_e32 v172, v171
	v_mov_b32_e32 v170, v169
	v_mov_b32_e32 v168, v161
	v_mul_f32_e32 v115, v116, v115
	v_mul_f32_e32 v116, 0x3fcc422a, v117
	v_mul_f32_e32 v116, v116, v122
	v_mul_f32_e32 v116, 0xbfb8aa3b, v116
	v_exp_f32_e32 v116, v116
	v_mul_f32_e32 v122, 0x3d372713, v118
	v_fma_f32 v122, v118, v122, 1.0
	v_mov_b32_e32 v160, v159
	v_add_f32_e32 v116, 1.0, v116
	v_rcp_f32_e32 v116, v116
	v_mov_b32_e32 v158, v157
	v_permlane32_swap_b32_e32 v175, v176
	v_mul_f32_e32 v116, v117, v116
	v_mul_f32_e32 v117, 0x3fcc422a, v118
	v_mul_f32_e32 v117, v117, v122
	v_mul_f32_e32 v117, 0xbfb8aa3b, v117
	v_exp_f32_e32 v117, v117
	v_mul_f32_e32 v122, 0x3d372713, v119
	v_fma_f32 v122, v119, v122, 1.0
	v_permlane32_swap_b32_e32 v173, v174
	v_add_f32_e32 v117, 1.0, v117
	v_rcp_f32_e32 v117, v117
	v_permlane32_swap_b32_e32 v171, v172
	v_permlane32_swap_b32_e32 v169, v170
	v_mul_f32_e32 v117, v118, v117
	v_mul_f32_e32 v118, 0x3fcc422a, v119
	v_mul_f32_e32 v118, v118, v122
	v_mul_f32_e32 v118, 0xbfb8aa3b, v118
	v_exp_f32_e32 v118, v118
	v_mul_f32_e32 v122, 0x3d372713, v120
	v_fma_f32 v122, v120, v122, 1.0
	v_permlane32_swap_b32_e32 v161, v168
	v_add_f32_e32 v118, 1.0, v118
	v_rcp_f32_e32 v118, v118
	v_permlane32_swap_b32_e32 v159, v160
	v_permlane32_swap_b32_e32 v157, v158
	v_mul_f32_e32 v118, v119, v118
	v_mul_f32_e32 v119, 0x3fcc422a, v120
	v_mul_f32_e32 v119, v119, v122
	v_mul_f32_e32 v119, 0xbfb8aa3b, v119
	v_exp_f32_e32 v119, v119
	v_mul_f32_e32 v122, 0x3d372713, v121
	v_fma_f32 v122, v121, v122, 1.0
	v_add_f32_e32 v119, 1.0, v119
	v_rcp_f32_e32 v119, v119
	s_nop 0
	v_mul_f32_e32 v119, v120, v119
	v_mul_f32_e32 v120, 0x3fcc422a, v121
	v_mul_f32_e32 v120, v120, v122
	v_mul_f32_e32 v120, 0xbfb8aa3b, v120
	v_exp_f32_e32 v120, v120
	v_mul_f32_e32 v122, v116, v116
	v_fmac_f32_e32 v122, v115, v115
	v_add_f32_e32 v120, 1.0, v120
	v_rcp_f32_e32 v120, v120
	s_nop 0
	v_mul_f32_e32 v120, v121, v120
	v_mul_f32_e32 v121, v114, v114
	v_fmac_f32_e32 v121, v0, v0
	v_add_f32_e32 v121, v121, v122
	v_mul_f32_e32 v122, v118, v118
	v_mul_f32_e32 v123, v120, v120
	v_fmac_f32_e32 v122, v117, v117
	v_fmac_f32_e32 v123, v119, v119
	v_add_f32_e32 v122, v122, v123
	v_add_f32_e32 v121, v121, v122
	v_add_f32_e32 v121, v177, v121
	v_cvt_pk_bf16_f32 v114, v0, v114
	v_mov_b32_e32 v0, v121
	s_nop 1
	v_permlane16_swap_b32_e32 v121, v0
	v_add_f32_e32 v0, v121, v0
	v_cvt_pk_bf16_f32 v115, v115, v116
	v_cvt_pk_bf16_f32 v116, v117, v118
	v_cvt_pk_bf16_f32 v117, v119, v120
	ds_bpermute_b32 v114, v255, v114
	ds_bpermute_b32 v115, v255, v115
	ds_bpermute_b32 v116, v255, v116
	ds_bpermute_b32 v117, v255, v117
	v_lshl_add_u64 v[154:155], v[154:155], 0, v[208:209]
	s_waitcnt lgkmcnt(4)
	global_store_dwordx4 v[154:155], v[250:253], off
	s_waitcnt lgkmcnt(0)
	global_store_dwordx4 v[154:155], v[114:117], off offset:256
	s_nop 1
	v_mov_b32_e32 v114, v0
	s_nop 1
	v_permlane32_swap_b32_e32 v0, v114
	s_and_saveexec_b64 s[0:1], s[2:3]
	s_cbranch_execz .LBB0_175
	v_add_f32_e32 v0, v0, v114
	v_lshlrev_b64 v[114:115], 7, v[150:151]
	s_lshl_b32 s36, s12, 2
	v_lshl_add_u64 v[114:115], v[138:139], 0, v[114:115]
	s_mov_b32 s37, s40
	v_lshl_add_u64 v[114:115], s[36:37], 2, v[114:115]
	s_lshl_b32 s36, s28, 2
	v_lshl_add_u64 v[114:115], v[114:115], 0, s[36:37]
	global_store_dword v[114:115], v0, off offset:-128
.LBB0_175:
	s_or_b64 exec, exec, s[0:1]
	v_add_f32_e32 v0, v175, v176
	v_fmamk_f32 v0, v0, 0x3a000000, v240
	v_rsq_f32_e32 v0, v0
	v_or_b32_e32 v114, 16, v150
	v_ashrrev_i32_e32 v115, 31, v114
	v_lshlrev_b64 v[116:117], 13, v[114:115]
	v_pk_mul_f32 v[106:107], v[106:107], v[0:1] op_sel_hi:[1,0]
	v_pk_mul_f32 v[108:109], v[108:109], v[0:1] op_sel_hi:[1,0]
	v_mul_f32_e32 v119, 0x3d372713, v106
	v_mul_f32_e32 v118, 0x3fcc422a, v106
	v_fma_f32 v119, v106, v119, 1.0
	v_mul_f32_e32 v118, v118, v119
	v_mul_f32_e32 v118, 0xbfb8aa3b, v118
	v_exp_f32_e32 v118, v118
	v_mul_f32_e32 v119, 0x3d372713, v107
	v_fma_f32 v119, v107, v119, 1.0
	v_pk_mul_f32 v[110:111], v[110:111], v[0:1] op_sel_hi:[1,0]
	v_add_f32_e32 v118, 1.0, v118
	v_rcp_f32_e32 v118, v118
	v_pk_mul_f32 v[112:113], v[112:113], v[0:1] op_sel_hi:[1,0]
	v_lshl_add_u64 v[116:117], v[152:153], 0, v[116:117]
	v_pk_mul_f32 v[98:99], v[98:99], v[0:1] op_sel_hi:[1,0]
	v_mul_f32_e32 v106, v106, v118
	v_mul_f32_e32 v118, 0x3fcc422a, v107
	v_mul_f32_e32 v118, v118, v119
	v_mul_f32_e32 v118, 0xbfb8aa3b, v118
	v_exp_f32_e32 v118, v118
	v_mul_f32_e32 v119, 0x3d372713, v108
	v_fma_f32 v119, v108, v119, 1.0
	v_pk_mul_f32 v[100:101], v[100:101], v[0:1] op_sel_hi:[1,0]
	v_add_f32_e32 v118, 1.0, v118
	v_rcp_f32_e32 v118, v118
	v_pk_mul_f32 v[104:105], v[104:105], v[0:1] op_sel_hi:[1,0]
	v_pk_mul_f32 v[102:103], v[102:103], v[0:1] op_sel_hi:[1,0]
	v_mul_f32_e32 v0, 0x3fcc422a, v98
	v_mul_f32_e32 v107, v107, v118
	v_mul_f32_e32 v118, 0x3fcc422a, v108
	v_mul_f32_e32 v118, v118, v119
	v_mul_f32_e32 v118, 0xbfb8aa3b, v118
	v_exp_f32_e32 v118, v118
	v_mul_f32_e32 v119, 0x3d372713, v109
	v_fma_f32 v119, v109, v119, 1.0
	v_add_f32_e32 v118, 1.0, v118
	v_rcp_f32_e32 v118, v118
	s_nop 0
	v_mul_f32_e32 v108, v108, v118
	v_mul_f32_e32 v118, 0x3fcc422a, v109
	v_mul_f32_e32 v118, v118, v119
	v_mul_f32_e32 v118, 0xbfb8aa3b, v118
	v_exp_f32_e32 v118, v118
	v_mul_f32_e32 v119, 0x3d372713, v110
	v_fma_f32 v119, v110, v119, 1.0
	v_add_f32_e32 v118, 1.0, v118
	v_rcp_f32_e32 v118, v118
	s_nop 0
	v_mul_f32_e32 v109, v109, v118
	v_mul_f32_e32 v118, 0x3fcc422a, v110
	v_mul_f32_e32 v118, v118, v119
	v_mul_f32_e32 v118, 0xbfb8aa3b, v118
	v_exp_f32_e32 v118, v118
	v_mul_f32_e32 v119, 0x3d372713, v111
	v_fma_f32 v119, v111, v119, 1.0
	v_add_f32_e32 v118, 1.0, v118
	v_rcp_f32_e32 v118, v118
	s_nop 0
	v_mul_f32_e32 v110, v110, v118
	v_mul_f32_e32 v118, 0x3fcc422a, v111
	v_mul_f32_e32 v118, v118, v119
	v_mul_f32_e32 v118, 0xbfb8aa3b, v118
	v_exp_f32_e32 v118, v118
	v_mul_f32_e32 v119, 0x3d372713, v112
	v_fma_f32 v119, v112, v119, 1.0
	v_add_f32_e32 v118, 1.0, v118
	v_rcp_f32_e32 v118, v118
	s_nop 0
	v_mul_f32_e32 v111, v111, v118
	v_mul_f32_e32 v118, 0x3fcc422a, v112
	v_mul_f32_e32 v118, v118, v119
	v_mul_f32_e32 v118, 0xbfb8aa3b, v118
	v_exp_f32_e32 v118, v118
	v_mul_f32_e32 v119, 0x3d372713, v113
	v_fma_f32 v119, v113, v119, 1.0
	v_add_f32_e32 v118, 1.0, v118
	v_rcp_f32_e32 v118, v118
	s_nop 0
	v_mul_f32_e32 v112, v112, v118
	v_mul_f32_e32 v118, 0x3fcc422a, v113
	v_mul_f32_e32 v118, v118, v119
	v_mul_f32_e32 v118, 0xbfb8aa3b, v118
	v_exp_f32_e32 v118, v118
	v_mul_f32_e32 v119, v109, v109
	v_fmac_f32_e32 v119, v108, v108
	v_add_f32_e32 v118, 1.0, v118
	v_rcp_f32_e32 v118, v118
	s_nop 0
	v_mul_f32_e32 v113, v113, v118
	v_mul_f32_e32 v118, v107, v107
	v_fmac_f32_e32 v118, v106, v106
	v_cvt_pk_bf16_f32 v106, v106, v107
	v_cvt_pk_bf16_f32 v107, v108, v109
	v_cvt_pk_bf16_f32 v108, v110, v111
	v_cvt_pk_bf16_f32 v109, v112, v113
	ds_bpermute_b32 v250, v255, v106
	ds_bpermute_b32 v251, v255, v107
	ds_bpermute_b32 v252, v255, v108
	ds_bpermute_b32 v253, v255, v109
	v_add_f32_e32 v118, v118, v119
	v_mul_f32_e32 v119, v111, v111
	v_mul_f32_e32 v106, 0x3d372713, v98
	v_fma_f32 v106, v98, v106, 1.0
	v_mul_f32_e32 v0, v0, v106
	v_mul_f32_e32 v0, 0xbfb8aa3b, v0
	v_exp_f32_e32 v0, v0
	v_mul_f32_e32 v106, 0x3d372713, v99
	v_fma_f32 v106, v99, v106, 1.0
	v_mul_f32_e32 v120, v113, v113
	v_add_f32_e32 v0, 1.0, v0
	v_rcp_f32_e32 v0, v0
	v_fmac_f32_e32 v119, v110, v110
	v_fmac_f32_e32 v120, v112, v112
	v_add_f32_e32 v119, v119, v120
	v_mul_f32_e32 v0, v98, v0
	v_mul_f32_e32 v98, 0x3fcc422a, v99
	v_mul_f32_e32 v98, v98, v106
	v_mul_f32_e32 v98, 0xbfb8aa3b, v98
	v_exp_f32_e32 v98, v98
	v_mul_f32_e32 v106, 0x3d372713, v100
	v_fma_f32 v106, v100, v106, 1.0
	v_add_f32_e32 v118, v118, v119
	v_add_f32_e32 v98, 1.0, v98
	v_rcp_f32_e32 v98, v98
	s_nop 0
	v_mul_f32_e32 v98, v99, v98
	v_mul_f32_e32 v99, 0x3fcc422a, v100
	v_mul_f32_e32 v99, v99, v106
	v_mul_f32_e32 v99, 0xbfb8aa3b, v99
	v_exp_f32_e32 v99, v99
	v_mul_f32_e32 v106, 0x3d372713, v101
	v_fma_f32 v106, v101, v106, 1.0
	v_add_f32_e32 v99, 1.0, v99
	v_rcp_f32_e32 v99, v99
	s_nop 0
	v_mul_f32_e32 v99, v100, v99
	v_mul_f32_e32 v100, 0x3fcc422a, v101
	v_mul_f32_e32 v100, v100, v106
	v_mul_f32_e32 v100, 0xbfb8aa3b, v100
	v_exp_f32_e32 v100, v100
	v_mul_f32_e32 v106, 0x3d372713, v102
	v_fma_f32 v106, v102, v106, 1.0
	v_add_f32_e32 v100, 1.0, v100
	v_rcp_f32_e32 v100, v100
	s_nop 0
	v_mul_f32_e32 v100, v101, v100
	v_mul_f32_e32 v101, 0x3fcc422a, v102
	v_mul_f32_e32 v101, v101, v106
	v_mul_f32_e32 v101, 0xbfb8aa3b, v101
	v_exp_f32_e32 v101, v101
	v_mul_f32_e32 v106, 0x3d372713, v103
	v_fma_f32 v106, v103, v106, 1.0
	v_add_f32_e32 v101, 1.0, v101
	v_rcp_f32_e32 v101, v101
	s_nop 0
	v_mul_f32_e32 v101, v102, v101
	v_mul_f32_e32 v102, 0x3fcc422a, v103
	v_mul_f32_e32 v102, v102, v106
	v_mul_f32_e32 v102, 0xbfb8aa3b, v102
	v_exp_f32_e32 v102, v102
	v_mul_f32_e32 v106, 0x3d372713, v104
	v_fma_f32 v106, v104, v106, 1.0
	v_add_f32_e32 v102, 1.0, v102
	v_rcp_f32_e32 v102, v102
	s_nop 0
	v_mul_f32_e32 v102, v103, v102
	v_mul_f32_e32 v103, 0x3fcc422a, v104
	v_mul_f32_e32 v103, v103, v106
	v_mul_f32_e32 v103, 0xbfb8aa3b, v103
	v_exp_f32_e32 v103, v103
	v_mul_f32_e32 v106, 0x3d372713, v105
	v_fma_f32 v106, v105, v106, 1.0
	v_add_f32_e32 v103, 1.0, v103
	v_rcp_f32_e32 v103, v103
	s_nop 0
	v_mul_f32_e32 v103, v104, v103
	v_mul_f32_e32 v104, 0x3fcc422a, v105
	v_mul_f32_e32 v104, v104, v106
	v_mul_f32_e32 v104, 0xbfb8aa3b, v104
	v_exp_f32_e32 v104, v104
	v_mul_f32_e32 v106, v100, v100
	v_fmac_f32_e32 v106, v99, v99
	v_add_f32_e32 v104, 1.0, v104
	v_rcp_f32_e32 v104, v104
	s_nop 0
	v_mul_f32_e32 v104, v105, v104
	v_mul_f32_e32 v105, v98, v98
	v_fmac_f32_e32 v105, v0, v0
	v_add_f32_e32 v105, v105, v106
	v_mul_f32_e32 v106, v102, v102
	v_mul_f32_e32 v107, v104, v104
	v_fmac_f32_e32 v106, v101, v101
	v_fmac_f32_e32 v107, v103, v103
	v_add_f32_e32 v106, v106, v107
	v_add_f32_e32 v105, v105, v106
	v_add_f32_e32 v105, v118, v105
	v_cvt_pk_bf16_f32 v98, v0, v98
	v_mov_b32_e32 v0, v105
	s_nop 1
	v_permlane16_swap_b32_e32 v105, v0
	v_add_f32_e32 v0, v105, v0
	v_cvt_pk_bf16_f32 v99, v99, v100
	v_cvt_pk_bf16_f32 v100, v101, v102
	v_cvt_pk_bf16_f32 v101, v103, v104
	ds_bpermute_b32 v98, v255, v98
	ds_bpermute_b32 v99, v255, v99
	ds_bpermute_b32 v100, v255, v100
	ds_bpermute_b32 v101, v255, v101
	v_lshl_add_u64 v[116:117], v[116:117], 0, v[208:209]
	s_waitcnt lgkmcnt(4)
	global_store_dwordx4 v[116:117], v[250:253], off
	s_waitcnt lgkmcnt(0)
	global_store_dwordx4 v[116:117], v[98:101], off offset:256
	s_nop 1
	v_mov_b32_e32 v98, v0
	s_nop 1
	v_permlane32_swap_b32_e32 v0, v98
	s_and_saveexec_b64 s[0:1], s[2:3]
	s_cbranch_execz .LBB0_177
	v_add_f32_e32 v0, v0, v98
	v_lshlrev_b64 v[98:99], 7, v[114:115]
	s_lshl_b32 s36, s12, 2
	v_lshl_add_u64 v[98:99], v[138:139], 0, v[98:99]
	s_mov_b32 s37, s40
	v_lshl_add_u64 v[98:99], s[36:37], 2, v[98:99]
	s_lshl_b32 s36, s28, 2
	v_lshl_add_u64 v[98:99], v[98:99], 0, s[36:37]
	global_store_dword v[98:99], v0, off offset:-128
.LBB0_177:
	s_or_b64 exec, exec, s[0:1]
	v_add_f32_e32 v0, v173, v174
	v_fmamk_f32 v0, v0, 0x3a000000, v240
	v_rsq_f32_e32 v0, v0
	v_or_b32_e32 v98, 32, v150
	v_ashrrev_i32_e32 v99, 31, v98
	v_lshlrev_b64 v[100:101], 13, v[98:99]
	v_pk_mul_f32 v[90:91], v[90:91], v[0:1] op_sel_hi:[1,0]
	v_pk_mul_f32 v[92:93], v[92:93], v[0:1] op_sel_hi:[1,0]
	v_mul_f32_e32 v103, 0x3d372713, v90
	v_mul_f32_e32 v102, 0x3fcc422a, v90
	v_fma_f32 v103, v90, v103, 1.0
	v_mul_f32_e32 v102, v102, v103
	v_mul_f32_e32 v102, 0xbfb8aa3b, v102
	v_exp_f32_e32 v102, v102
	v_mul_f32_e32 v103, 0x3d372713, v91
	v_fma_f32 v103, v91, v103, 1.0
	v_pk_mul_f32 v[94:95], v[94:95], v[0:1] op_sel_hi:[1,0]
	v_add_f32_e32 v102, 1.0, v102
	v_rcp_f32_e32 v102, v102
	v_pk_mul_f32 v[96:97], v[96:97], v[0:1] op_sel_hi:[1,0]
	v_lshl_add_u64 v[100:101], v[152:153], 0, v[100:101]
	v_pk_mul_f32 v[82:83], v[82:83], v[0:1] op_sel_hi:[1,0]
	v_mul_f32_e32 v90, v90, v102
	v_mul_f32_e32 v102, 0x3fcc422a, v91
	v_mul_f32_e32 v102, v102, v103
	v_mul_f32_e32 v102, 0xbfb8aa3b, v102
	v_exp_f32_e32 v102, v102
	v_mul_f32_e32 v103, 0x3d372713, v92
	v_fma_f32 v103, v92, v103, 1.0
	v_pk_mul_f32 v[84:85], v[84:85], v[0:1] op_sel_hi:[1,0]
	v_add_f32_e32 v102, 1.0, v102
	v_rcp_f32_e32 v102, v102
	v_pk_mul_f32 v[88:89], v[88:89], v[0:1] op_sel_hi:[1,0]
	v_pk_mul_f32 v[86:87], v[86:87], v[0:1] op_sel_hi:[1,0]
	v_mul_f32_e32 v0, 0x3fcc422a, v82
	v_mul_f32_e32 v91, v91, v102
	v_mul_f32_e32 v102, 0x3fcc422a, v92
	v_mul_f32_e32 v102, v102, v103
	v_mul_f32_e32 v102, 0xbfb8aa3b, v102
	v_exp_f32_e32 v102, v102
	v_mul_f32_e32 v103, 0x3d372713, v93
	v_fma_f32 v103, v93, v103, 1.0
	v_add_f32_e32 v102, 1.0, v102
	v_rcp_f32_e32 v102, v102
	s_nop 0
	v_mul_f32_e32 v92, v92, v102
	v_mul_f32_e32 v102, 0x3fcc422a, v93
	v_mul_f32_e32 v102, v102, v103
	v_mul_f32_e32 v102, 0xbfb8aa3b, v102
	v_exp_f32_e32 v102, v102
	v_mul_f32_e32 v103, 0x3d372713, v94
	v_fma_f32 v103, v94, v103, 1.0
	v_add_f32_e32 v102, 1.0, v102
	v_rcp_f32_e32 v102, v102
	s_nop 0
	v_mul_f32_e32 v93, v93, v102
	v_mul_f32_e32 v102, 0x3fcc422a, v94
	v_mul_f32_e32 v102, v102, v103
	v_mul_f32_e32 v102, 0xbfb8aa3b, v102
	v_exp_f32_e32 v102, v102
	v_mul_f32_e32 v103, 0x3d372713, v95
	v_fma_f32 v103, v95, v103, 1.0
	v_add_f32_e32 v102, 1.0, v102
	v_rcp_f32_e32 v102, v102
	s_nop 0
	v_mul_f32_e32 v94, v94, v102
	v_mul_f32_e32 v102, 0x3fcc422a, v95
	v_mul_f32_e32 v102, v102, v103
	v_mul_f32_e32 v102, 0xbfb8aa3b, v102
	v_exp_f32_e32 v102, v102
	v_mul_f32_e32 v103, 0x3d372713, v96
	v_fma_f32 v103, v96, v103, 1.0
	v_add_f32_e32 v102, 1.0, v102
	v_rcp_f32_e32 v102, v102
	s_nop 0
	v_mul_f32_e32 v95, v95, v102
	v_mul_f32_e32 v102, 0x3fcc422a, v96
	v_mul_f32_e32 v102, v102, v103
	v_mul_f32_e32 v102, 0xbfb8aa3b, v102
	v_exp_f32_e32 v102, v102
	v_mul_f32_e32 v103, 0x3d372713, v97
	v_fma_f32 v103, v97, v103, 1.0
	v_add_f32_e32 v102, 1.0, v102
	v_rcp_f32_e32 v102, v102
	s_nop 0
	v_mul_f32_e32 v96, v96, v102
	v_mul_f32_e32 v102, 0x3fcc422a, v97
	v_mul_f32_e32 v102, v102, v103
	v_mul_f32_e32 v102, 0xbfb8aa3b, v102
	v_exp_f32_e32 v102, v102
	v_mul_f32_e32 v103, v93, v93
	v_fmac_f32_e32 v103, v92, v92
	v_add_f32_e32 v102, 1.0, v102
	v_rcp_f32_e32 v102, v102
	s_nop 0
	v_mul_f32_e32 v97, v97, v102
	v_mul_f32_e32 v102, v91, v91
	v_fmac_f32_e32 v102, v90, v90
	v_cvt_pk_bf16_f32 v90, v90, v91
	v_cvt_pk_bf16_f32 v91, v92, v93
	v_cvt_pk_bf16_f32 v92, v94, v95
	v_cvt_pk_bf16_f32 v93, v96, v97
	ds_bpermute_b32 v250, v255, v90
	ds_bpermute_b32 v251, v255, v91
	ds_bpermute_b32 v252, v255, v92
	ds_bpermute_b32 v253, v255, v93
	v_add_f32_e32 v102, v102, v103
	v_mul_f32_e32 v103, v95, v95
	v_mul_f32_e32 v90, 0x3d372713, v82
	v_fma_f32 v90, v82, v90, 1.0
	v_mul_f32_e32 v0, v0, v90
	v_mul_f32_e32 v0, 0xbfb8aa3b, v0
	v_exp_f32_e32 v0, v0
	v_mul_f32_e32 v90, 0x3d372713, v83
	v_fma_f32 v90, v83, v90, 1.0
	v_mul_f32_e32 v104, v97, v97
	v_add_f32_e32 v0, 1.0, v0
	v_rcp_f32_e32 v0, v0
	v_fmac_f32_e32 v103, v94, v94
	v_fmac_f32_e32 v104, v96, v96
	v_add_f32_e32 v103, v103, v104
	v_mul_f32_e32 v0, v82, v0
	v_mul_f32_e32 v82, 0x3fcc422a, v83
	v_mul_f32_e32 v82, v82, v90
	v_mul_f32_e32 v82, 0xbfb8aa3b, v82
	v_exp_f32_e32 v82, v82
	v_mul_f32_e32 v90, 0x3d372713, v84
	v_fma_f32 v90, v84, v90, 1.0
	v_add_f32_e32 v102, v102, v103
	v_add_f32_e32 v82, 1.0, v82
	v_rcp_f32_e32 v82, v82
	s_nop 0
	v_mul_f32_e32 v82, v83, v82
	v_mul_f32_e32 v83, 0x3fcc422a, v84
	v_mul_f32_e32 v83, v83, v90
	v_mul_f32_e32 v83, 0xbfb8aa3b, v83
	v_exp_f32_e32 v83, v83
	v_mul_f32_e32 v90, 0x3d372713, v85
	v_fma_f32 v90, v85, v90, 1.0
	v_add_f32_e32 v83, 1.0, v83
	v_rcp_f32_e32 v83, v83
	s_nop 0
	v_mul_f32_e32 v83, v84, v83
	v_mul_f32_e32 v84, 0x3fcc422a, v85
	v_mul_f32_e32 v84, v84, v90
	v_mul_f32_e32 v84, 0xbfb8aa3b, v84
	v_exp_f32_e32 v84, v84
	v_mul_f32_e32 v90, 0x3d372713, v86
	v_fma_f32 v90, v86, v90, 1.0
	v_add_f32_e32 v84, 1.0, v84
	v_rcp_f32_e32 v84, v84
	s_nop 0
	v_mul_f32_e32 v84, v85, v84
	v_mul_f32_e32 v85, 0x3fcc422a, v86
	v_mul_f32_e32 v85, v85, v90
	v_mul_f32_e32 v85, 0xbfb8aa3b, v85
	v_exp_f32_e32 v85, v85
	v_mul_f32_e32 v90, 0x3d372713, v87
	v_fma_f32 v90, v87, v90, 1.0
	v_add_f32_e32 v85, 1.0, v85
	v_rcp_f32_e32 v85, v85
	s_nop 0
	v_mul_f32_e32 v85, v86, v85
	v_mul_f32_e32 v86, 0x3fcc422a, v87
	v_mul_f32_e32 v86, v86, v90
	v_mul_f32_e32 v86, 0xbfb8aa3b, v86
	v_exp_f32_e32 v86, v86
	v_mul_f32_e32 v90, 0x3d372713, v88
	v_fma_f32 v90, v88, v90, 1.0
	v_add_f32_e32 v86, 1.0, v86
	v_rcp_f32_e32 v86, v86
	s_nop 0
	v_mul_f32_e32 v86, v87, v86
	v_mul_f32_e32 v87, 0x3fcc422a, v88
	v_mul_f32_e32 v87, v87, v90
	v_mul_f32_e32 v87, 0xbfb8aa3b, v87
	v_exp_f32_e32 v87, v87
	v_mul_f32_e32 v90, 0x3d372713, v89
	v_fma_f32 v90, v89, v90, 1.0
	v_add_f32_e32 v87, 1.0, v87
	v_rcp_f32_e32 v87, v87
	s_nop 0
	v_mul_f32_e32 v87, v88, v87
	v_mul_f32_e32 v88, 0x3fcc422a, v89
	v_mul_f32_e32 v88, v88, v90
	v_mul_f32_e32 v88, 0xbfb8aa3b, v88
	v_exp_f32_e32 v88, v88
	v_mul_f32_e32 v90, v84, v84
	v_fmac_f32_e32 v90, v83, v83
	v_add_f32_e32 v88, 1.0, v88
	v_rcp_f32_e32 v88, v88
	s_nop 0
	v_mul_f32_e32 v88, v89, v88
	v_mul_f32_e32 v89, v82, v82
	v_fmac_f32_e32 v89, v0, v0
	v_add_f32_e32 v89, v89, v90
	v_mul_f32_e32 v90, v86, v86
	v_mul_f32_e32 v91, v88, v88
	v_fmac_f32_e32 v90, v85, v85
	v_fmac_f32_e32 v91, v87, v87
	v_add_f32_e32 v90, v90, v91
	v_add_f32_e32 v89, v89, v90
	v_add_f32_e32 v89, v102, v89
	v_cvt_pk_bf16_f32 v82, v0, v82
	v_mov_b32_e32 v0, v89
	s_nop 1
	v_permlane16_swap_b32_e32 v89, v0
	v_add_f32_e32 v0, v89, v0
	v_cvt_pk_bf16_f32 v83, v83, v84
	v_cvt_pk_bf16_f32 v84, v85, v86
	v_cvt_pk_bf16_f32 v85, v87, v88
	ds_bpermute_b32 v82, v255, v82
	ds_bpermute_b32 v83, v255, v83
	ds_bpermute_b32 v84, v255, v84
	ds_bpermute_b32 v85, v255, v85
	v_lshl_add_u64 v[100:101], v[100:101], 0, v[208:209]
	s_waitcnt lgkmcnt(4)
	global_store_dwordx4 v[100:101], v[250:253], off
	s_waitcnt lgkmcnt(0)
	global_store_dwordx4 v[100:101], v[82:85], off offset:256
	s_nop 1
	v_mov_b32_e32 v82, v0
	s_nop 1
	v_permlane32_swap_b32_e32 v0, v82
	s_and_saveexec_b64 s[0:1], s[2:3]
	s_cbranch_execz .LBB0_179
	v_add_f32_e32 v0, v0, v82
	v_lshlrev_b64 v[82:83], 7, v[98:99]
	s_lshl_b32 s36, s12, 2
	v_lshl_add_u64 v[82:83], v[138:139], 0, v[82:83]
	s_mov_b32 s37, s40
	v_lshl_add_u64 v[82:83], s[36:37], 2, v[82:83]
	s_lshl_b32 s36, s28, 2
	v_lshl_add_u64 v[82:83], v[82:83], 0, s[36:37]
	global_store_dword v[82:83], v0, off offset:-128
.LBB0_179:
	s_or_b64 exec, exec, s[0:1]
	v_add_f32_e32 v0, v171, v172
	v_fmamk_f32 v0, v0, 0x3a000000, v240
	v_rsq_f32_e32 v0, v0
	v_or_b32_e32 v82, 48, v150
	v_ashrrev_i32_e32 v83, 31, v82
	v_lshlrev_b64 v[84:85], 13, v[82:83]
	v_pk_mul_f32 v[74:75], v[74:75], v[0:1] op_sel_hi:[1,0]
	v_pk_mul_f32 v[76:77], v[76:77], v[0:1] op_sel_hi:[1,0]
	v_mul_f32_e32 v87, 0x3d372713, v74
	v_mul_f32_e32 v86, 0x3fcc422a, v74
	v_fma_f32 v87, v74, v87, 1.0
	v_mul_f32_e32 v86, v86, v87
	v_mul_f32_e32 v86, 0xbfb8aa3b, v86
	v_exp_f32_e32 v86, v86
	v_mul_f32_e32 v87, 0x3d372713, v75
	v_fma_f32 v87, v75, v87, 1.0
	v_pk_mul_f32 v[78:79], v[78:79], v[0:1] op_sel_hi:[1,0]
	v_add_f32_e32 v86, 1.0, v86
	v_rcp_f32_e32 v86, v86
	v_pk_mul_f32 v[80:81], v[80:81], v[0:1] op_sel_hi:[1,0]
	v_lshl_add_u64 v[84:85], v[152:153], 0, v[84:85]
	v_pk_mul_f32 v[66:67], v[66:67], v[0:1] op_sel_hi:[1,0]
	v_mul_f32_e32 v74, v74, v86
	v_mul_f32_e32 v86, 0x3fcc422a, v75
	v_mul_f32_e32 v86, v86, v87
	v_mul_f32_e32 v86, 0xbfb8aa3b, v86
	v_exp_f32_e32 v86, v86
	v_mul_f32_e32 v87, 0x3d372713, v76
	v_fma_f32 v87, v76, v87, 1.0
	v_pk_mul_f32 v[68:69], v[68:69], v[0:1] op_sel_hi:[1,0]
	v_add_f32_e32 v86, 1.0, v86
	v_rcp_f32_e32 v86, v86
	v_pk_mul_f32 v[72:73], v[72:73], v[0:1] op_sel_hi:[1,0]
	v_pk_mul_f32 v[70:71], v[70:71], v[0:1] op_sel_hi:[1,0]
	v_mul_f32_e32 v0, 0x3fcc422a, v66
	v_mul_f32_e32 v75, v75, v86
	v_mul_f32_e32 v86, 0x3fcc422a, v76
	v_mul_f32_e32 v86, v86, v87
	v_mul_f32_e32 v86, 0xbfb8aa3b, v86
	v_exp_f32_e32 v86, v86
	v_mul_f32_e32 v87, 0x3d372713, v77
	v_fma_f32 v87, v77, v87, 1.0
	v_add_f32_e32 v86, 1.0, v86
	v_rcp_f32_e32 v86, v86
	s_nop 0
	v_mul_f32_e32 v76, v76, v86
	v_mul_f32_e32 v86, 0x3fcc422a, v77
	v_mul_f32_e32 v86, v86, v87
	v_mul_f32_e32 v86, 0xbfb8aa3b, v86
	v_exp_f32_e32 v86, v86
	v_mul_f32_e32 v87, 0x3d372713, v78
	v_fma_f32 v87, v78, v87, 1.0
	v_add_f32_e32 v86, 1.0, v86
	v_rcp_f32_e32 v86, v86
	s_nop 0
	v_mul_f32_e32 v77, v77, v86
	v_mul_f32_e32 v86, 0x3fcc422a, v78
	v_mul_f32_e32 v86, v86, v87
	v_mul_f32_e32 v86, 0xbfb8aa3b, v86
	v_exp_f32_e32 v86, v86
	v_mul_f32_e32 v87, 0x3d372713, v79
	v_fma_f32 v87, v79, v87, 1.0
	v_add_f32_e32 v86, 1.0, v86
	v_rcp_f32_e32 v86, v86
	s_nop 0
	v_mul_f32_e32 v78, v78, v86
	v_mul_f32_e32 v86, 0x3fcc422a, v79
	v_mul_f32_e32 v86, v86, v87
	v_mul_f32_e32 v86, 0xbfb8aa3b, v86
	v_exp_f32_e32 v86, v86
	v_mul_f32_e32 v87, 0x3d372713, v80
	v_fma_f32 v87, v80, v87, 1.0
	v_add_f32_e32 v86, 1.0, v86
	v_rcp_f32_e32 v86, v86
	s_nop 0
	v_mul_f32_e32 v79, v79, v86
	v_mul_f32_e32 v86, 0x3fcc422a, v80
	v_mul_f32_e32 v86, v86, v87
	v_mul_f32_e32 v86, 0xbfb8aa3b, v86
	v_exp_f32_e32 v86, v86
	v_mul_f32_e32 v87, 0x3d372713, v81
	v_fma_f32 v87, v81, v87, 1.0
	v_add_f32_e32 v86, 1.0, v86
	v_rcp_f32_e32 v86, v86
	s_nop 0
	v_mul_f32_e32 v80, v80, v86
	v_mul_f32_e32 v86, 0x3fcc422a, v81
	v_mul_f32_e32 v86, v86, v87
	v_mul_f32_e32 v86, 0xbfb8aa3b, v86
	v_exp_f32_e32 v86, v86
	v_mul_f32_e32 v87, v77, v77
	v_fmac_f32_e32 v87, v76, v76
	v_add_f32_e32 v86, 1.0, v86
	v_rcp_f32_e32 v86, v86
	s_nop 0
	v_mul_f32_e32 v81, v81, v86
	v_mul_f32_e32 v86, v75, v75
	v_fmac_f32_e32 v86, v74, v74
	v_cvt_pk_bf16_f32 v74, v74, v75
	v_cvt_pk_bf16_f32 v75, v76, v77
	v_cvt_pk_bf16_f32 v76, v78, v79
	v_cvt_pk_bf16_f32 v77, v80, v81
	ds_bpermute_b32 v250, v255, v74
	ds_bpermute_b32 v251, v255, v75
	ds_bpermute_b32 v252, v255, v76
	ds_bpermute_b32 v253, v255, v77
	v_add_f32_e32 v86, v86, v87
	v_mul_f32_e32 v87, v79, v79
	v_mul_f32_e32 v74, 0x3d372713, v66
	v_fma_f32 v74, v66, v74, 1.0
	v_mul_f32_e32 v0, v0, v74
	v_mul_f32_e32 v0, 0xbfb8aa3b, v0
	v_exp_f32_e32 v0, v0
	v_mul_f32_e32 v74, 0x3d372713, v67
	v_fma_f32 v74, v67, v74, 1.0
	v_mul_f32_e32 v88, v81, v81
	v_add_f32_e32 v0, 1.0, v0
	v_rcp_f32_e32 v0, v0
	v_fmac_f32_e32 v87, v78, v78
	v_fmac_f32_e32 v88, v80, v80
	v_add_f32_e32 v87, v87, v88
	v_mul_f32_e32 v0, v66, v0
	v_mul_f32_e32 v66, 0x3fcc422a, v67
	v_mul_f32_e32 v66, v66, v74
	v_mul_f32_e32 v66, 0xbfb8aa3b, v66
	v_exp_f32_e32 v66, v66
	v_mul_f32_e32 v74, 0x3d372713, v68
	v_fma_f32 v74, v68, v74, 1.0
	v_add_f32_e32 v86, v86, v87
	v_add_f32_e32 v66, 1.0, v66
	v_rcp_f32_e32 v66, v66
	s_nop 0
	v_mul_f32_e32 v66, v67, v66
	v_mul_f32_e32 v67, 0x3fcc422a, v68
	v_mul_f32_e32 v67, v67, v74
	v_mul_f32_e32 v67, 0xbfb8aa3b, v67
	v_exp_f32_e32 v67, v67
	v_mul_f32_e32 v74, 0x3d372713, v69
	v_fma_f32 v74, v69, v74, 1.0
	v_add_f32_e32 v67, 1.0, v67
	v_rcp_f32_e32 v67, v67
	s_nop 0
	v_mul_f32_e32 v67, v68, v67
	v_mul_f32_e32 v68, 0x3fcc422a, v69
	v_mul_f32_e32 v68, v68, v74
	v_mul_f32_e32 v68, 0xbfb8aa3b, v68
	v_exp_f32_e32 v68, v68
	v_mul_f32_e32 v74, 0x3d372713, v70
	v_fma_f32 v74, v70, v74, 1.0
	v_add_f32_e32 v68, 1.0, v68
	v_rcp_f32_e32 v68, v68
	s_nop 0
	v_mul_f32_e32 v68, v69, v68
	v_mul_f32_e32 v69, 0x3fcc422a, v70
	v_mul_f32_e32 v69, v69, v74
	v_mul_f32_e32 v69, 0xbfb8aa3b, v69
	v_exp_f32_e32 v69, v69
	v_mul_f32_e32 v74, 0x3d372713, v71
	v_fma_f32 v74, v71, v74, 1.0
	v_add_f32_e32 v69, 1.0, v69
	v_rcp_f32_e32 v69, v69
	s_nop 0
	v_mul_f32_e32 v69, v70, v69
	v_mul_f32_e32 v70, 0x3fcc422a, v71
	v_mul_f32_e32 v70, v70, v74
	v_mul_f32_e32 v70, 0xbfb8aa3b, v70
	v_exp_f32_e32 v70, v70
	v_mul_f32_e32 v74, 0x3d372713, v72
	v_fma_f32 v74, v72, v74, 1.0
	v_add_f32_e32 v70, 1.0, v70
	v_rcp_f32_e32 v70, v70
	s_nop 0
	v_mul_f32_e32 v70, v71, v70
	v_mul_f32_e32 v71, 0x3fcc422a, v72
	v_mul_f32_e32 v71, v71, v74
	v_mul_f32_e32 v71, 0xbfb8aa3b, v71
	v_exp_f32_e32 v71, v71
	v_mul_f32_e32 v74, 0x3d372713, v73
	v_fma_f32 v74, v73, v74, 1.0
	v_add_f32_e32 v71, 1.0, v71
	v_rcp_f32_e32 v71, v71
	s_nop 0
	v_mul_f32_e32 v71, v72, v71
	v_mul_f32_e32 v72, 0x3fcc422a, v73
	v_mul_f32_e32 v72, v72, v74
	v_mul_f32_e32 v72, 0xbfb8aa3b, v72
	v_exp_f32_e32 v72, v72
	v_mul_f32_e32 v74, v68, v68
	v_fmac_f32_e32 v74, v67, v67
	v_add_f32_e32 v72, 1.0, v72
	v_rcp_f32_e32 v72, v72
	s_nop 0
	v_mul_f32_e32 v72, v73, v72
	v_mul_f32_e32 v73, v66, v66
	v_fmac_f32_e32 v73, v0, v0
	v_add_f32_e32 v73, v73, v74
	v_mul_f32_e32 v74, v70, v70
	v_mul_f32_e32 v75, v72, v72
	v_fmac_f32_e32 v74, v69, v69
	v_fmac_f32_e32 v75, v71, v71
	v_add_f32_e32 v74, v74, v75
	v_add_f32_e32 v73, v73, v74
	v_add_f32_e32 v73, v86, v73
	v_cvt_pk_bf16_f32 v66, v0, v66
	v_mov_b32_e32 v0, v73
	s_nop 1
	v_permlane16_swap_b32_e32 v73, v0
	v_add_f32_e32 v0, v73, v0
	v_cvt_pk_bf16_f32 v67, v67, v68
	v_cvt_pk_bf16_f32 v68, v69, v70
	v_cvt_pk_bf16_f32 v69, v71, v72
	ds_bpermute_b32 v66, v255, v66
	ds_bpermute_b32 v67, v255, v67
	ds_bpermute_b32 v68, v255, v68
	ds_bpermute_b32 v69, v255, v69
	v_lshl_add_u64 v[84:85], v[84:85], 0, v[208:209]
	s_waitcnt lgkmcnt(4)
	global_store_dwordx4 v[84:85], v[250:253], off
	s_waitcnt lgkmcnt(0)
	global_store_dwordx4 v[84:85], v[66:69], off offset:256
	s_nop 1
	v_mov_b32_e32 v66, v0
	s_nop 1
	v_permlane32_swap_b32_e32 v0, v66
	s_and_saveexec_b64 s[0:1], s[2:3]
	s_cbranch_execz .LBB0_181
	v_add_f32_e32 v0, v0, v66
	v_lshlrev_b64 v[66:67], 7, v[82:83]
	s_lshl_b32 s36, s12, 2
	v_lshl_add_u64 v[66:67], v[138:139], 0, v[66:67]
	s_mov_b32 s37, s40
	v_lshl_add_u64 v[66:67], s[36:37], 2, v[66:67]
	s_lshl_b32 s36, s28, 2
	v_lshl_add_u64 v[66:67], v[66:67], 0, s[36:37]
	global_store_dword v[66:67], v0, off offset:-128
.LBB0_181:
	s_or_b64 exec, exec, s[0:1]
	v_add_f32_e32 v0, v169, v170
	v_fmamk_f32 v0, v0, 0x3a000000, v240
	v_rsq_f32_e32 v0, v0
	v_add_u32_e32 v66, 0x80, v150
	v_ashrrev_i32_e32 v67, 31, v66
	v_lshlrev_b64 v[68:69], 13, v[66:67]
	v_pk_mul_f32 v[58:59], v[58:59], v[0:1] op_sel_hi:[1,0]
	v_pk_mul_f32 v[60:61], v[60:61], v[0:1] op_sel_hi:[1,0]
	v_mul_f32_e32 v71, 0x3d372713, v58
	v_mul_f32_e32 v70, 0x3fcc422a, v58
	v_fma_f32 v71, v58, v71, 1.0
	v_mul_f32_e32 v70, v70, v71
	v_mul_f32_e32 v70, 0xbfb8aa3b, v70
	v_exp_f32_e32 v70, v70
	v_mul_f32_e32 v71, 0x3d372713, v59
	v_fma_f32 v71, v59, v71, 1.0
	v_pk_mul_f32 v[62:63], v[62:63], v[0:1] op_sel_hi:[1,0]
	v_add_f32_e32 v70, 1.0, v70
	v_rcp_f32_e32 v70, v70
	v_pk_mul_f32 v[64:65], v[64:65], v[0:1] op_sel_hi:[1,0]
	v_lshl_add_u64 v[68:69], v[152:153], 0, v[68:69]
	v_pk_mul_f32 v[50:51], v[50:51], v[0:1] op_sel_hi:[1,0]
	v_mul_f32_e32 v58, v58, v70
	v_mul_f32_e32 v70, 0x3fcc422a, v59
	v_mul_f32_e32 v70, v70, v71
	v_mul_f32_e32 v70, 0xbfb8aa3b, v70
	v_exp_f32_e32 v70, v70
	v_mul_f32_e32 v71, 0x3d372713, v60
	v_fma_f32 v71, v60, v71, 1.0
	v_pk_mul_f32 v[52:53], v[52:53], v[0:1] op_sel_hi:[1,0]
	v_add_f32_e32 v70, 1.0, v70
	v_rcp_f32_e32 v70, v70
	v_pk_mul_f32 v[56:57], v[56:57], v[0:1] op_sel_hi:[1,0]
	v_pk_mul_f32 v[54:55], v[54:55], v[0:1] op_sel_hi:[1,0]
	v_mul_f32_e32 v0, 0x3fcc422a, v50
	v_mul_f32_e32 v59, v59, v70
	v_mul_f32_e32 v70, 0x3fcc422a, v60
	v_mul_f32_e32 v70, v70, v71
	v_mul_f32_e32 v70, 0xbfb8aa3b, v70
	v_exp_f32_e32 v70, v70
	v_mul_f32_e32 v71, 0x3d372713, v61
	v_fma_f32 v71, v61, v71, 1.0
	v_add_f32_e32 v70, 1.0, v70
	v_rcp_f32_e32 v70, v70
	s_nop 0
	v_mul_f32_e32 v60, v60, v70
	v_mul_f32_e32 v70, 0x3fcc422a, v61
	v_mul_f32_e32 v70, v70, v71
	v_mul_f32_e32 v70, 0xbfb8aa3b, v70
	v_exp_f32_e32 v70, v70
	v_mul_f32_e32 v71, 0x3d372713, v62
	v_fma_f32 v71, v62, v71, 1.0
	v_add_f32_e32 v70, 1.0, v70
	v_rcp_f32_e32 v70, v70
	s_nop 0
	v_mul_f32_e32 v61, v61, v70
	v_mul_f32_e32 v70, 0x3fcc422a, v62
	v_mul_f32_e32 v70, v70, v71
	v_mul_f32_e32 v70, 0xbfb8aa3b, v70
	v_exp_f32_e32 v70, v70
	v_mul_f32_e32 v71, 0x3d372713, v63
	v_fma_f32 v71, v63, v71, 1.0
	v_add_f32_e32 v70, 1.0, v70
	v_rcp_f32_e32 v70, v70
	s_nop 0
	v_mul_f32_e32 v62, v62, v70
	v_mul_f32_e32 v70, 0x3fcc422a, v63
	v_mul_f32_e32 v70, v70, v71
	v_mul_f32_e32 v70, 0xbfb8aa3b, v70
	v_exp_f32_e32 v70, v70
	v_mul_f32_e32 v71, 0x3d372713, v64
	v_fma_f32 v71, v64, v71, 1.0
	v_add_f32_e32 v70, 1.0, v70
	v_rcp_f32_e32 v70, v70
	s_nop 0
	v_mul_f32_e32 v63, v63, v70
	v_mul_f32_e32 v70, 0x3fcc422a, v64
	v_mul_f32_e32 v70, v70, v71
	v_mul_f32_e32 v70, 0xbfb8aa3b, v70
	v_exp_f32_e32 v70, v70
	v_mul_f32_e32 v71, 0x3d372713, v65
	v_fma_f32 v71, v65, v71, 1.0
	v_add_f32_e32 v70, 1.0, v70
	v_rcp_f32_e32 v70, v70
	s_nop 0
	v_mul_f32_e32 v64, v64, v70
	v_mul_f32_e32 v70, 0x3fcc422a, v65
	v_mul_f32_e32 v70, v70, v71
	v_mul_f32_e32 v70, 0xbfb8aa3b, v70
	v_exp_f32_e32 v70, v70
	v_mul_f32_e32 v71, v61, v61
	v_fmac_f32_e32 v71, v60, v60
	v_add_f32_e32 v70, 1.0, v70
	v_rcp_f32_e32 v70, v70
	s_nop 0
	v_mul_f32_e32 v65, v65, v70
	v_mul_f32_e32 v70, v59, v59
	v_fmac_f32_e32 v70, v58, v58
	v_cvt_pk_bf16_f32 v58, v58, v59
	v_cvt_pk_bf16_f32 v59, v60, v61
	v_cvt_pk_bf16_f32 v60, v62, v63
	v_cvt_pk_bf16_f32 v61, v64, v65
	ds_bpermute_b32 v250, v255, v58
	ds_bpermute_b32 v251, v255, v59
	ds_bpermute_b32 v252, v255, v60
	ds_bpermute_b32 v253, v255, v61
	v_add_f32_e32 v70, v70, v71
	v_mul_f32_e32 v71, v63, v63
	v_mul_f32_e32 v58, 0x3d372713, v50
	v_fma_f32 v58, v50, v58, 1.0
	v_mul_f32_e32 v0, v0, v58
	v_mul_f32_e32 v0, 0xbfb8aa3b, v0
	v_exp_f32_e32 v0, v0
	v_mul_f32_e32 v58, 0x3d372713, v51
	v_fma_f32 v58, v51, v58, 1.0
	v_mul_f32_e32 v72, v65, v65
	v_add_f32_e32 v0, 1.0, v0
	v_rcp_f32_e32 v0, v0
	v_fmac_f32_e32 v71, v62, v62
	v_fmac_f32_e32 v72, v64, v64
	v_add_f32_e32 v71, v71, v72
	v_mul_f32_e32 v0, v50, v0
	v_mul_f32_e32 v50, 0x3fcc422a, v51
	v_mul_f32_e32 v50, v50, v58
	v_mul_f32_e32 v50, 0xbfb8aa3b, v50
	v_exp_f32_e32 v50, v50
	v_mul_f32_e32 v58, 0x3d372713, v52
	v_fma_f32 v58, v52, v58, 1.0
	v_add_f32_e32 v70, v70, v71
	v_add_f32_e32 v50, 1.0, v50
	v_rcp_f32_e32 v50, v50
	s_nop 0
	v_mul_f32_e32 v50, v51, v50
	v_mul_f32_e32 v51, 0x3fcc422a, v52
	v_mul_f32_e32 v51, v51, v58
	v_mul_f32_e32 v51, 0xbfb8aa3b, v51
	v_exp_f32_e32 v51, v51
	v_mul_f32_e32 v58, 0x3d372713, v53
	v_fma_f32 v58, v53, v58, 1.0
	v_add_f32_e32 v51, 1.0, v51
	v_rcp_f32_e32 v51, v51
	s_nop 0
	v_mul_f32_e32 v51, v52, v51
	v_mul_f32_e32 v52, 0x3fcc422a, v53
	v_mul_f32_e32 v52, v52, v58
	v_mul_f32_e32 v52, 0xbfb8aa3b, v52
	v_exp_f32_e32 v52, v52
	v_mul_f32_e32 v58, 0x3d372713, v54
	v_fma_f32 v58, v54, v58, 1.0
	v_add_f32_e32 v52, 1.0, v52
	v_rcp_f32_e32 v52, v52
	s_nop 0
	v_mul_f32_e32 v52, v53, v52
	v_mul_f32_e32 v53, 0x3fcc422a, v54
	v_mul_f32_e32 v53, v53, v58
	v_mul_f32_e32 v53, 0xbfb8aa3b, v53
	v_exp_f32_e32 v53, v53
	v_mul_f32_e32 v58, 0x3d372713, v55
	v_fma_f32 v58, v55, v58, 1.0
	v_add_f32_e32 v53, 1.0, v53
	v_rcp_f32_e32 v53, v53
	s_nop 0
	v_mul_f32_e32 v53, v54, v53
	v_mul_f32_e32 v54, 0x3fcc422a, v55
	v_mul_f32_e32 v54, v54, v58
	v_mul_f32_e32 v54, 0xbfb8aa3b, v54
	v_exp_f32_e32 v54, v54
	v_mul_f32_e32 v58, 0x3d372713, v56
	v_fma_f32 v58, v56, v58, 1.0
	v_add_f32_e32 v54, 1.0, v54
	v_rcp_f32_e32 v54, v54
	s_nop 0
	v_mul_f32_e32 v54, v55, v54
	v_mul_f32_e32 v55, 0x3fcc422a, v56
	v_mul_f32_e32 v55, v55, v58
	v_mul_f32_e32 v55, 0xbfb8aa3b, v55
	v_exp_f32_e32 v55, v55
	v_mul_f32_e32 v58, 0x3d372713, v57
	v_fma_f32 v58, v57, v58, 1.0
	v_add_f32_e32 v55, 1.0, v55
	v_rcp_f32_e32 v55, v55
	s_nop 0
	v_mul_f32_e32 v55, v56, v55
	v_mul_f32_e32 v56, 0x3fcc422a, v57
	v_mul_f32_e32 v56, v56, v58
	v_mul_f32_e32 v56, 0xbfb8aa3b, v56
	v_exp_f32_e32 v56, v56
	v_mul_f32_e32 v58, v52, v52
	v_fmac_f32_e32 v58, v51, v51
	v_add_f32_e32 v56, 1.0, v56
	v_rcp_f32_e32 v56, v56
	s_nop 0
	v_mul_f32_e32 v56, v57, v56
	v_mul_f32_e32 v57, v50, v50
	v_fmac_f32_e32 v57, v0, v0
	v_add_f32_e32 v57, v57, v58
	v_mul_f32_e32 v58, v54, v54
	v_mul_f32_e32 v59, v56, v56
	v_fmac_f32_e32 v58, v53, v53
	v_fmac_f32_e32 v59, v55, v55
	v_add_f32_e32 v58, v58, v59
	v_add_f32_e32 v57, v57, v58
	v_add_f32_e32 v57, v70, v57
	v_cvt_pk_bf16_f32 v50, v0, v50
	v_mov_b32_e32 v0, v57
	s_nop 1
	v_permlane16_swap_b32_e32 v57, v0
	v_add_f32_e32 v0, v57, v0
	v_cvt_pk_bf16_f32 v51, v51, v52
	v_cvt_pk_bf16_f32 v52, v53, v54
	v_cvt_pk_bf16_f32 v53, v55, v56
	ds_bpermute_b32 v50, v255, v50
	ds_bpermute_b32 v51, v255, v51
	ds_bpermute_b32 v52, v255, v52
	ds_bpermute_b32 v53, v255, v53
	v_lshl_add_u64 v[68:69], v[68:69], 0, v[208:209]
	s_waitcnt lgkmcnt(4)
	global_store_dwordx4 v[68:69], v[250:253], off
	s_waitcnt lgkmcnt(0)
	global_store_dwordx4 v[68:69], v[50:53], off offset:256
	s_nop 1
	v_mov_b32_e32 v50, v0
	s_nop 1
	v_permlane32_swap_b32_e32 v0, v50
	s_and_saveexec_b64 s[0:1], s[2:3]
	s_cbranch_execz .LBB0_183
	v_add_f32_e32 v0, v0, v50
	v_lshlrev_b64 v[50:51], 7, v[66:67]
	s_lshl_b32 s36, s12, 2
	v_lshl_add_u64 v[50:51], v[138:139], 0, v[50:51]
	s_mov_b32 s37, s40
	v_lshl_add_u64 v[50:51], s[36:37], 2, v[50:51]
	s_lshl_b32 s36, s28, 2
	v_lshl_add_u64 v[50:51], v[50:51], 0, s[36:37]
	global_store_dword v[50:51], v0, off offset:-128
.LBB0_183:
	s_or_b64 exec, exec, s[0:1]
	v_add_f32_e32 v0, v161, v168
	v_fmamk_f32 v0, v0, 0x3a000000, v240
	v_rsq_f32_e32 v0, v0
	v_add_u32_e32 v50, 0x90, v150
	v_ashrrev_i32_e32 v51, 31, v50
	v_lshlrev_b64 v[52:53], 13, v[50:51]
	v_pk_mul_f32 v[42:43], v[42:43], v[0:1] op_sel_hi:[1,0]
	v_pk_mul_f32 v[44:45], v[44:45], v[0:1] op_sel_hi:[1,0]
	v_mul_f32_e32 v55, 0x3d372713, v42
	v_mul_f32_e32 v54, 0x3fcc422a, v42
	v_fma_f32 v55, v42, v55, 1.0
	v_mul_f32_e32 v54, v54, v55
	v_mul_f32_e32 v54, 0xbfb8aa3b, v54
	v_exp_f32_e32 v54, v54
	v_mul_f32_e32 v55, 0x3d372713, v43
	v_fma_f32 v55, v43, v55, 1.0
	v_pk_mul_f32 v[46:47], v[46:47], v[0:1] op_sel_hi:[1,0]
	v_add_f32_e32 v54, 1.0, v54
	v_rcp_f32_e32 v54, v54
	v_pk_mul_f32 v[48:49], v[48:49], v[0:1] op_sel_hi:[1,0]
	v_lshl_add_u64 v[52:53], v[152:153], 0, v[52:53]
	v_pk_mul_f32 v[34:35], v[34:35], v[0:1] op_sel_hi:[1,0]
	v_mul_f32_e32 v42, v42, v54
	v_mul_f32_e32 v54, 0x3fcc422a, v43
	v_mul_f32_e32 v54, v54, v55
	v_mul_f32_e32 v54, 0xbfb8aa3b, v54
	v_exp_f32_e32 v54, v54
	v_mul_f32_e32 v55, 0x3d372713, v44
	v_fma_f32 v55, v44, v55, 1.0
	v_pk_mul_f32 v[36:37], v[36:37], v[0:1] op_sel_hi:[1,0]
	v_add_f32_e32 v54, 1.0, v54
	v_rcp_f32_e32 v54, v54
	v_pk_mul_f32 v[40:41], v[40:41], v[0:1] op_sel_hi:[1,0]
	v_pk_mul_f32 v[38:39], v[38:39], v[0:1] op_sel_hi:[1,0]
	v_mul_f32_e32 v0, 0x3fcc422a, v34
	v_mul_f32_e32 v43, v43, v54
	v_mul_f32_e32 v54, 0x3fcc422a, v44
	v_mul_f32_e32 v54, v54, v55
	v_mul_f32_e32 v54, 0xbfb8aa3b, v54
	v_exp_f32_e32 v54, v54
	v_mul_f32_e32 v55, 0x3d372713, v45
	v_fma_f32 v55, v45, v55, 1.0
	v_add_f32_e32 v54, 1.0, v54
	v_rcp_f32_e32 v54, v54
	s_nop 0
	v_mul_f32_e32 v44, v44, v54
	v_mul_f32_e32 v54, 0x3fcc422a, v45
	v_mul_f32_e32 v54, v54, v55
	v_mul_f32_e32 v54, 0xbfb8aa3b, v54
	v_exp_f32_e32 v54, v54
	v_mul_f32_e32 v55, 0x3d372713, v46
	v_fma_f32 v55, v46, v55, 1.0
	v_add_f32_e32 v54, 1.0, v54
	v_rcp_f32_e32 v54, v54
	s_nop 0
	v_mul_f32_e32 v45, v45, v54
	v_mul_f32_e32 v54, 0x3fcc422a, v46
	v_mul_f32_e32 v54, v54, v55
	v_mul_f32_e32 v54, 0xbfb8aa3b, v54
	v_exp_f32_e32 v54, v54
	v_mul_f32_e32 v55, 0x3d372713, v47
	v_fma_f32 v55, v47, v55, 1.0
	v_add_f32_e32 v54, 1.0, v54
	v_rcp_f32_e32 v54, v54
	s_nop 0
	v_mul_f32_e32 v46, v46, v54
	v_mul_f32_e32 v54, 0x3fcc422a, v47
	v_mul_f32_e32 v54, v54, v55
	v_mul_f32_e32 v54, 0xbfb8aa3b, v54
	v_exp_f32_e32 v54, v54
	v_mul_f32_e32 v55, 0x3d372713, v48
	v_fma_f32 v55, v48, v55, 1.0
	v_add_f32_e32 v54, 1.0, v54
	v_rcp_f32_e32 v54, v54
	s_nop 0
	v_mul_f32_e32 v47, v47, v54
	v_mul_f32_e32 v54, 0x3fcc422a, v48
	v_mul_f32_e32 v54, v54, v55
	v_mul_f32_e32 v54, 0xbfb8aa3b, v54
	v_exp_f32_e32 v54, v54
	v_mul_f32_e32 v55, 0x3d372713, v49
	v_fma_f32 v55, v49, v55, 1.0
	v_add_f32_e32 v54, 1.0, v54
	v_rcp_f32_e32 v54, v54
	s_nop 0
	v_mul_f32_e32 v48, v48, v54
	v_mul_f32_e32 v54, 0x3fcc422a, v49
	v_mul_f32_e32 v54, v54, v55
	v_mul_f32_e32 v54, 0xbfb8aa3b, v54
	v_exp_f32_e32 v54, v54
	v_mul_f32_e32 v55, v45, v45
	v_fmac_f32_e32 v55, v44, v44
	v_add_f32_e32 v54, 1.0, v54
	v_rcp_f32_e32 v54, v54
	s_nop 0
	v_mul_f32_e32 v49, v49, v54
	v_mul_f32_e32 v54, v43, v43
	v_fmac_f32_e32 v54, v42, v42
	v_cvt_pk_bf16_f32 v42, v42, v43
	v_cvt_pk_bf16_f32 v43, v44, v45
	v_cvt_pk_bf16_f32 v44, v46, v47
	v_cvt_pk_bf16_f32 v45, v48, v49
	ds_bpermute_b32 v250, v255, v42
	ds_bpermute_b32 v251, v255, v43
	ds_bpermute_b32 v252, v255, v44
	ds_bpermute_b32 v253, v255, v45
	v_add_f32_e32 v54, v54, v55
	v_mul_f32_e32 v55, v47, v47
	v_mul_f32_e32 v42, 0x3d372713, v34
	v_fma_f32 v42, v34, v42, 1.0
	v_mul_f32_e32 v0, v0, v42
	v_mul_f32_e32 v0, 0xbfb8aa3b, v0
	v_exp_f32_e32 v0, v0
	v_mul_f32_e32 v42, 0x3d372713, v35
	v_fma_f32 v42, v35, v42, 1.0
	v_mul_f32_e32 v56, v49, v49
	v_add_f32_e32 v0, 1.0, v0
	v_rcp_f32_e32 v0, v0
	v_fmac_f32_e32 v55, v46, v46
	v_fmac_f32_e32 v56, v48, v48
	v_add_f32_e32 v55, v55, v56
	v_mul_f32_e32 v0, v34, v0
	v_mul_f32_e32 v34, 0x3fcc422a, v35
	v_mul_f32_e32 v34, v34, v42
	v_mul_f32_e32 v34, 0xbfb8aa3b, v34
	v_exp_f32_e32 v34, v34
	v_mul_f32_e32 v42, 0x3d372713, v36
	v_fma_f32 v42, v36, v42, 1.0
	v_add_f32_e32 v54, v54, v55
	v_add_f32_e32 v34, 1.0, v34
	v_rcp_f32_e32 v34, v34
	s_nop 0
	v_mul_f32_e32 v34, v35, v34
	v_mul_f32_e32 v35, 0x3fcc422a, v36
	v_mul_f32_e32 v35, v35, v42
	v_mul_f32_e32 v35, 0xbfb8aa3b, v35
	v_exp_f32_e32 v35, v35
	v_mul_f32_e32 v42, 0x3d372713, v37
	v_fma_f32 v42, v37, v42, 1.0
	v_add_f32_e32 v35, 1.0, v35
	v_rcp_f32_e32 v35, v35
	s_nop 0
	v_mul_f32_e32 v35, v36, v35
	v_mul_f32_e32 v36, 0x3fcc422a, v37
	v_mul_f32_e32 v36, v36, v42
	v_mul_f32_e32 v36, 0xbfb8aa3b, v36
	v_exp_f32_e32 v36, v36
	v_mul_f32_e32 v42, 0x3d372713, v38
	v_fma_f32 v42, v38, v42, 1.0
	v_add_f32_e32 v36, 1.0, v36
	v_rcp_f32_e32 v36, v36
	s_nop 0
	v_mul_f32_e32 v36, v37, v36
	v_mul_f32_e32 v37, 0x3fcc422a, v38
	v_mul_f32_e32 v37, v37, v42
	v_mul_f32_e32 v37, 0xbfb8aa3b, v37
	v_exp_f32_e32 v37, v37
	v_mul_f32_e32 v42, 0x3d372713, v39
	v_fma_f32 v42, v39, v42, 1.0
	v_add_f32_e32 v37, 1.0, v37
	v_rcp_f32_e32 v37, v37
	s_nop 0
	v_mul_f32_e32 v37, v38, v37
	v_mul_f32_e32 v38, 0x3fcc422a, v39
	v_mul_f32_e32 v38, v38, v42
	v_mul_f32_e32 v38, 0xbfb8aa3b, v38
	v_exp_f32_e32 v38, v38
	v_mul_f32_e32 v42, 0x3d372713, v40
	v_fma_f32 v42, v40, v42, 1.0
	v_add_f32_e32 v38, 1.0, v38
	v_rcp_f32_e32 v38, v38
	s_nop 0
	v_mul_f32_e32 v38, v39, v38
	v_mul_f32_e32 v39, 0x3fcc422a, v40
	v_mul_f32_e32 v39, v39, v42
	v_mul_f32_e32 v39, 0xbfb8aa3b, v39
	v_exp_f32_e32 v39, v39
	v_mul_f32_e32 v42, 0x3d372713, v41
	v_fma_f32 v42, v41, v42, 1.0
	v_add_f32_e32 v39, 1.0, v39
	v_rcp_f32_e32 v39, v39
	s_nop 0
	v_mul_f32_e32 v39, v40, v39
	v_mul_f32_e32 v40, 0x3fcc422a, v41
	v_mul_f32_e32 v40, v40, v42
	v_mul_f32_e32 v40, 0xbfb8aa3b, v40
	v_exp_f32_e32 v40, v40
	v_mul_f32_e32 v42, v36, v36
	v_fmac_f32_e32 v42, v35, v35
	v_add_f32_e32 v40, 1.0, v40
	v_rcp_f32_e32 v40, v40
	s_nop 0
	v_mul_f32_e32 v40, v41, v40
	v_mul_f32_e32 v41, v34, v34
	v_fmac_f32_e32 v41, v0, v0
	v_add_f32_e32 v41, v41, v42
	v_mul_f32_e32 v42, v38, v38
	v_mul_f32_e32 v43, v40, v40
	v_fmac_f32_e32 v42, v37, v37
	v_fmac_f32_e32 v43, v39, v39
	v_add_f32_e32 v42, v42, v43
	v_add_f32_e32 v41, v41, v42
	v_add_f32_e32 v41, v54, v41
	v_cvt_pk_bf16_f32 v34, v0, v34
	v_mov_b32_e32 v0, v41
	s_nop 1
	v_permlane16_swap_b32_e32 v41, v0
	v_add_f32_e32 v0, v41, v0
	v_cvt_pk_bf16_f32 v35, v35, v36
	v_cvt_pk_bf16_f32 v36, v37, v38
	v_cvt_pk_bf16_f32 v37, v39, v40
	ds_bpermute_b32 v34, v255, v34
	ds_bpermute_b32 v35, v255, v35
	ds_bpermute_b32 v36, v255, v36
	ds_bpermute_b32 v37, v255, v37
	v_lshl_add_u64 v[52:53], v[52:53], 0, v[208:209]
	s_waitcnt lgkmcnt(4)
	global_store_dwordx4 v[52:53], v[250:253], off
	s_waitcnt lgkmcnt(0)
	global_store_dwordx4 v[52:53], v[34:37], off offset:256
	s_nop 1
	v_mov_b32_e32 v34, v0
	s_nop 1
	v_permlane32_swap_b32_e32 v0, v34
	s_and_saveexec_b64 s[0:1], s[2:3]
	s_cbranch_execz .LBB0_185
	v_add_f32_e32 v0, v0, v34
	v_lshlrev_b64 v[34:35], 7, v[50:51]
	s_lshl_b32 s36, s12, 2
	v_lshl_add_u64 v[34:35], v[138:139], 0, v[34:35]
	s_mov_b32 s37, s40
	v_lshl_add_u64 v[34:35], s[36:37], 2, v[34:35]
	s_lshl_b32 s36, s28, 2
	v_lshl_add_u64 v[34:35], v[34:35], 0, s[36:37]
	global_store_dword v[34:35], v0, off offset:-128
.LBB0_185:
	s_or_b64 exec, exec, s[0:1]
	v_add_f32_e32 v0, v159, v160
	v_fmamk_f32 v0, v0, 0x3a000000, v240
	v_rsq_f32_e32 v0, v0
	v_add_u32_e32 v34, 0xa0, v150
	v_ashrrev_i32_e32 v35, 31, v34
	v_lshlrev_b64 v[36:37], 13, v[34:35]
	v_pk_mul_f32 v[26:27], v[26:27], v[0:1] op_sel_hi:[1,0]
	v_pk_mul_f32 v[28:29], v[28:29], v[0:1] op_sel_hi:[1,0]
	v_mul_f32_e32 v39, 0x3d372713, v26
	v_mul_f32_e32 v38, 0x3fcc422a, v26
	v_fma_f32 v39, v26, v39, 1.0
	v_mul_f32_e32 v38, v38, v39
	v_mul_f32_e32 v38, 0xbfb8aa3b, v38
	v_exp_f32_e32 v38, v38
	v_mul_f32_e32 v39, 0x3d372713, v27
	v_fma_f32 v39, v27, v39, 1.0
	v_pk_mul_f32 v[30:31], v[30:31], v[0:1] op_sel_hi:[1,0]
	v_add_f32_e32 v38, 1.0, v38
	v_rcp_f32_e32 v38, v38
	v_pk_mul_f32 v[32:33], v[32:33], v[0:1] op_sel_hi:[1,0]
	v_lshl_add_u64 v[36:37], v[152:153], 0, v[36:37]
	v_pk_mul_f32 v[18:19], v[18:19], v[0:1] op_sel_hi:[1,0]
	v_mul_f32_e32 v26, v26, v38
	v_mul_f32_e32 v38, 0x3fcc422a, v27
	v_mul_f32_e32 v38, v38, v39
	v_mul_f32_e32 v38, 0xbfb8aa3b, v38
	v_exp_f32_e32 v38, v38
	v_mul_f32_e32 v39, 0x3d372713, v28
	v_fma_f32 v39, v28, v39, 1.0
	v_pk_mul_f32 v[20:21], v[20:21], v[0:1] op_sel_hi:[1,0]
	v_add_f32_e32 v38, 1.0, v38
	v_rcp_f32_e32 v38, v38
	v_pk_mul_f32 v[24:25], v[24:25], v[0:1] op_sel_hi:[1,0]
	v_pk_mul_f32 v[22:23], v[22:23], v[0:1] op_sel_hi:[1,0]
	v_mul_f32_e32 v0, 0x3fcc422a, v18
	v_mul_f32_e32 v27, v27, v38
	v_mul_f32_e32 v38, 0x3fcc422a, v28
	v_mul_f32_e32 v38, v38, v39
	v_mul_f32_e32 v38, 0xbfb8aa3b, v38
	v_exp_f32_e32 v38, v38
	v_mul_f32_e32 v39, 0x3d372713, v29
	v_fma_f32 v39, v29, v39, 1.0
	v_add_f32_e32 v38, 1.0, v38
	v_rcp_f32_e32 v38, v38
	s_nop 0
	v_mul_f32_e32 v28, v28, v38
	v_mul_f32_e32 v38, 0x3fcc422a, v29
	v_mul_f32_e32 v38, v38, v39
	v_mul_f32_e32 v38, 0xbfb8aa3b, v38
	v_exp_f32_e32 v38, v38
	v_mul_f32_e32 v39, 0x3d372713, v30
	v_fma_f32 v39, v30, v39, 1.0
	v_add_f32_e32 v38, 1.0, v38
	v_rcp_f32_e32 v38, v38
	s_nop 0
	v_mul_f32_e32 v29, v29, v38
	v_mul_f32_e32 v38, 0x3fcc422a, v30
	v_mul_f32_e32 v38, v38, v39
	v_mul_f32_e32 v38, 0xbfb8aa3b, v38
	v_exp_f32_e32 v38, v38
	v_mul_f32_e32 v39, 0x3d372713, v31
	v_fma_f32 v39, v31, v39, 1.0
	v_add_f32_e32 v38, 1.0, v38
	v_rcp_f32_e32 v38, v38
	s_nop 0
	v_mul_f32_e32 v30, v30, v38
	v_mul_f32_e32 v38, 0x3fcc422a, v31
	v_mul_f32_e32 v38, v38, v39
	v_mul_f32_e32 v38, 0xbfb8aa3b, v38
	v_exp_f32_e32 v38, v38
	v_mul_f32_e32 v39, 0x3d372713, v32
	v_fma_f32 v39, v32, v39, 1.0
	v_add_f32_e32 v38, 1.0, v38
	v_rcp_f32_e32 v38, v38
	s_nop 0
	v_mul_f32_e32 v31, v31, v38
	v_mul_f32_e32 v38, 0x3fcc422a, v32
	v_mul_f32_e32 v38, v38, v39
	v_mul_f32_e32 v38, 0xbfb8aa3b, v38
	v_exp_f32_e32 v38, v38
	v_mul_f32_e32 v39, 0x3d372713, v33
	v_fma_f32 v39, v33, v39, 1.0
	v_add_f32_e32 v38, 1.0, v38
	v_rcp_f32_e32 v38, v38
	s_nop 0
	v_mul_f32_e32 v32, v32, v38
	v_mul_f32_e32 v38, 0x3fcc422a, v33
	v_mul_f32_e32 v38, v38, v39
	v_mul_f32_e32 v38, 0xbfb8aa3b, v38
	v_exp_f32_e32 v38, v38
	v_mul_f32_e32 v39, v29, v29
	v_fmac_f32_e32 v39, v28, v28
	v_add_f32_e32 v38, 1.0, v38
	v_rcp_f32_e32 v38, v38
	s_nop 0
	v_mul_f32_e32 v33, v33, v38
	v_mul_f32_e32 v38, v27, v27
	v_fmac_f32_e32 v38, v26, v26
	v_cvt_pk_bf16_f32 v26, v26, v27
	v_cvt_pk_bf16_f32 v27, v28, v29
	v_cvt_pk_bf16_f32 v28, v30, v31
	v_cvt_pk_bf16_f32 v29, v32, v33
	ds_bpermute_b32 v250, v255, v26
	ds_bpermute_b32 v251, v255, v27
	ds_bpermute_b32 v252, v255, v28
	ds_bpermute_b32 v253, v255, v29
	v_add_f32_e32 v38, v38, v39
	v_mul_f32_e32 v39, v31, v31
	v_mul_f32_e32 v26, 0x3d372713, v18
	v_fma_f32 v26, v18, v26, 1.0
	v_mul_f32_e32 v0, v0, v26
	v_mul_f32_e32 v0, 0xbfb8aa3b, v0
	v_exp_f32_e32 v0, v0
	v_mul_f32_e32 v26, 0x3d372713, v19
	v_fma_f32 v26, v19, v26, 1.0
	v_mul_f32_e32 v40, v33, v33
	v_add_f32_e32 v0, 1.0, v0
	v_rcp_f32_e32 v0, v0
	v_fmac_f32_e32 v39, v30, v30
	v_fmac_f32_e32 v40, v32, v32
	v_add_f32_e32 v39, v39, v40
	v_mul_f32_e32 v0, v18, v0
	v_mul_f32_e32 v18, 0x3fcc422a, v19
	v_mul_f32_e32 v18, v18, v26
	v_mul_f32_e32 v18, 0xbfb8aa3b, v18
	v_exp_f32_e32 v18, v18
	v_mul_f32_e32 v26, 0x3d372713, v20
	v_fma_f32 v26, v20, v26, 1.0
	v_add_f32_e32 v38, v38, v39
	v_add_f32_e32 v18, 1.0, v18
	v_rcp_f32_e32 v18, v18
	s_nop 0
	v_mul_f32_e32 v18, v19, v18
	v_mul_f32_e32 v19, 0x3fcc422a, v20
	v_mul_f32_e32 v19, v19, v26
	v_mul_f32_e32 v19, 0xbfb8aa3b, v19
	v_exp_f32_e32 v19, v19
	v_mul_f32_e32 v26, 0x3d372713, v21
	v_fma_f32 v26, v21, v26, 1.0
	v_add_f32_e32 v19, 1.0, v19
	v_rcp_f32_e32 v19, v19
	s_nop 0
	v_mul_f32_e32 v19, v20, v19
	v_mul_f32_e32 v20, 0x3fcc422a, v21
	v_mul_f32_e32 v20, v20, v26
	v_mul_f32_e32 v20, 0xbfb8aa3b, v20
	v_exp_f32_e32 v20, v20
	v_mul_f32_e32 v26, 0x3d372713, v22
	v_fma_f32 v26, v22, v26, 1.0
	v_add_f32_e32 v20, 1.0, v20
	v_rcp_f32_e32 v20, v20
	s_nop 0
	v_mul_f32_e32 v20, v21, v20
	v_mul_f32_e32 v21, 0x3fcc422a, v22
	v_mul_f32_e32 v21, v21, v26
	v_mul_f32_e32 v21, 0xbfb8aa3b, v21
	v_exp_f32_e32 v21, v21
	v_mul_f32_e32 v26, 0x3d372713, v23
	v_fma_f32 v26, v23, v26, 1.0
	v_add_f32_e32 v21, 1.0, v21
	v_rcp_f32_e32 v21, v21
	s_nop 0
	v_mul_f32_e32 v21, v22, v21
	v_mul_f32_e32 v22, 0x3fcc422a, v23
	v_mul_f32_e32 v22, v22, v26
	v_mul_f32_e32 v22, 0xbfb8aa3b, v22
	v_exp_f32_e32 v22, v22
	v_mul_f32_e32 v26, 0x3d372713, v24
	v_fma_f32 v26, v24, v26, 1.0
	v_add_f32_e32 v22, 1.0, v22
	v_rcp_f32_e32 v22, v22
	s_nop 0
	v_mul_f32_e32 v22, v23, v22
	v_mul_f32_e32 v23, 0x3fcc422a, v24
	v_mul_f32_e32 v23, v23, v26
	v_mul_f32_e32 v23, 0xbfb8aa3b, v23
	v_exp_f32_e32 v23, v23
	v_mul_f32_e32 v26, 0x3d372713, v25
	v_fma_f32 v26, v25, v26, 1.0
	v_add_f32_e32 v23, 1.0, v23
	v_rcp_f32_e32 v23, v23
	s_nop 0
	v_mul_f32_e32 v23, v24, v23
	v_mul_f32_e32 v24, 0x3fcc422a, v25
	v_mul_f32_e32 v24, v24, v26
	v_mul_f32_e32 v24, 0xbfb8aa3b, v24
	v_exp_f32_e32 v24, v24
	v_mul_f32_e32 v26, v20, v20
	v_fmac_f32_e32 v26, v19, v19
	v_add_f32_e32 v24, 1.0, v24
	v_rcp_f32_e32 v24, v24
	s_nop 0
	v_mul_f32_e32 v24, v25, v24
	v_mul_f32_e32 v25, v18, v18
	v_fmac_f32_e32 v25, v0, v0
	v_add_f32_e32 v25, v25, v26
	v_mul_f32_e32 v26, v22, v22
	v_mul_f32_e32 v27, v24, v24
	v_fmac_f32_e32 v26, v21, v21
	v_fmac_f32_e32 v27, v23, v23
	v_add_f32_e32 v26, v26, v27
	v_add_f32_e32 v25, v25, v26
	v_add_f32_e32 v25, v38, v25
	v_cvt_pk_bf16_f32 v18, v0, v18
	v_mov_b32_e32 v0, v25
	s_nop 1
	v_permlane16_swap_b32_e32 v25, v0
	v_add_f32_e32 v0, v25, v0
	v_cvt_pk_bf16_f32 v19, v19, v20
	v_cvt_pk_bf16_f32 v20, v21, v22
	v_cvt_pk_bf16_f32 v21, v23, v24
	ds_bpermute_b32 v18, v255, v18
	ds_bpermute_b32 v19, v255, v19
	ds_bpermute_b32 v20, v255, v20
	ds_bpermute_b32 v21, v255, v21
	v_lshl_add_u64 v[36:37], v[36:37], 0, v[208:209]
	s_waitcnt lgkmcnt(4)
	global_store_dwordx4 v[36:37], v[250:253], off
	s_waitcnt lgkmcnt(0)
	global_store_dwordx4 v[36:37], v[18:21], off offset:256
	s_nop 1
	v_mov_b32_e32 v18, v0
	s_nop 1
	v_permlane32_swap_b32_e32 v0, v18
	s_and_saveexec_b64 s[0:1], s[2:3]
	s_cbranch_execz .LBB0_187
	v_add_f32_e32 v0, v0, v18
	v_lshlrev_b64 v[18:19], 7, v[34:35]
	s_lshl_b32 s36, s12, 2
	v_lshl_add_u64 v[18:19], v[138:139], 0, v[18:19]
	s_mov_b32 s37, s40
	v_lshl_add_u64 v[18:19], s[36:37], 2, v[18:19]
	s_lshl_b32 s36, s28, 2
	v_lshl_add_u64 v[18:19], v[18:19], 0, s[36:37]
	global_store_dword v[18:19], v0, off offset:-128
.LBB0_187:
	s_or_b64 exec, exec, s[0:1]
	v_add_f32_e32 v0, v157, v158
	v_fmamk_f32 v0, v0, 0x3a000000, v240
	v_rsq_f32_e32 v0, v0
	v_add_u32_e32 v18, 0xb0, v150
	v_ashrrev_i32_e32 v19, 31, v18
	v_lshlrev_b64 v[20:21], 13, v[18:19]
	v_pk_mul_f32 v[10:11], v[10:11], v[0:1] op_sel_hi:[1,0]
	v_pk_mul_f32 v[12:13], v[12:13], v[0:1] op_sel_hi:[1,0]
	v_mul_f32_e32 v23, 0x3d372713, v10
	v_mul_f32_e32 v22, 0x3fcc422a, v10
	v_fma_f32 v23, v10, v23, 1.0
	v_mul_f32_e32 v22, v22, v23
	v_mul_f32_e32 v22, 0xbfb8aa3b, v22
	v_exp_f32_e32 v22, v22
	v_mul_f32_e32 v23, 0x3d372713, v11
	v_fma_f32 v23, v11, v23, 1.0
	v_pk_mul_f32 v[14:15], v[14:15], v[0:1] op_sel_hi:[1,0]
	v_add_f32_e32 v22, 1.0, v22
	v_rcp_f32_e32 v22, v22
	v_pk_mul_f32 v[16:17], v[16:17], v[0:1] op_sel_hi:[1,0]
	v_lshl_add_u64 v[20:21], v[152:153], 0, v[20:21]
	v_pk_mul_f32 v[2:3], v[2:3], v[0:1] op_sel_hi:[1,0]
	v_mul_f32_e32 v10, v10, v22
	v_mul_f32_e32 v22, 0x3fcc422a, v11
	v_mul_f32_e32 v22, v22, v23
	v_mul_f32_e32 v22, 0xbfb8aa3b, v22
	v_exp_f32_e32 v22, v22
	v_mul_f32_e32 v23, 0x3d372713, v12
	v_fma_f32 v23, v12, v23, 1.0
	v_pk_mul_f32 v[4:5], v[4:5], v[0:1] op_sel_hi:[1,0]
	v_add_f32_e32 v22, 1.0, v22
	v_rcp_f32_e32 v22, v22
	v_pk_mul_f32 v[8:9], v[8:9], v[0:1] op_sel_hi:[1,0]
	v_pk_mul_f32 v[6:7], v[6:7], v[0:1] op_sel_hi:[1,0]
	v_mul_f32_e32 v0, 0x3fcc422a, v2
	v_mul_f32_e32 v11, v11, v22
	v_mul_f32_e32 v22, 0x3fcc422a, v12
	v_mul_f32_e32 v22, v22, v23
	v_mul_f32_e32 v22, 0xbfb8aa3b, v22
	v_exp_f32_e32 v22, v22
	v_mul_f32_e32 v23, 0x3d372713, v13
	v_fma_f32 v23, v13, v23, 1.0
	v_add_f32_e32 v22, 1.0, v22
	v_rcp_f32_e32 v22, v22
	s_nop 0
	v_mul_f32_e32 v12, v12, v22
	v_mul_f32_e32 v22, 0x3fcc422a, v13
	v_mul_f32_e32 v22, v22, v23
	v_mul_f32_e32 v22, 0xbfb8aa3b, v22
	v_exp_f32_e32 v22, v22
	v_mul_f32_e32 v23, 0x3d372713, v14
	v_fma_f32 v23, v14, v23, 1.0
	v_add_f32_e32 v22, 1.0, v22
	v_rcp_f32_e32 v22, v22
	s_nop 0
	v_mul_f32_e32 v13, v13, v22
	v_mul_f32_e32 v22, 0x3fcc422a, v14
	v_mul_f32_e32 v22, v22, v23
	v_mul_f32_e32 v22, 0xbfb8aa3b, v22
	v_exp_f32_e32 v22, v22
	v_mul_f32_e32 v23, 0x3d372713, v15
	v_fma_f32 v23, v15, v23, 1.0
	v_add_f32_e32 v22, 1.0, v22
	v_rcp_f32_e32 v22, v22
	s_nop 0
	v_mul_f32_e32 v14, v14, v22
	v_mul_f32_e32 v22, 0x3fcc422a, v15
	v_mul_f32_e32 v22, v22, v23
	v_mul_f32_e32 v22, 0xbfb8aa3b, v22
	v_exp_f32_e32 v22, v22
	v_mul_f32_e32 v23, 0x3d372713, v16
	v_fma_f32 v23, v16, v23, 1.0
	v_add_f32_e32 v22, 1.0, v22
	v_rcp_f32_e32 v22, v22
	s_nop 0
	v_mul_f32_e32 v15, v15, v22
	v_mul_f32_e32 v22, 0x3fcc422a, v16
	v_mul_f32_e32 v22, v22, v23
	v_mul_f32_e32 v22, 0xbfb8aa3b, v22
	v_exp_f32_e32 v22, v22
	v_mul_f32_e32 v23, 0x3d372713, v17
	v_fma_f32 v23, v17, v23, 1.0
	v_add_f32_e32 v22, 1.0, v22
	v_rcp_f32_e32 v22, v22
	s_nop 0
	v_mul_f32_e32 v16, v16, v22
	v_mul_f32_e32 v22, 0x3fcc422a, v17
	v_mul_f32_e32 v22, v22, v23
	v_mul_f32_e32 v22, 0xbfb8aa3b, v22
	v_exp_f32_e32 v22, v22
	v_mul_f32_e32 v23, v13, v13
	v_fmac_f32_e32 v23, v12, v12
	v_add_f32_e32 v22, 1.0, v22
	v_rcp_f32_e32 v22, v22
	s_nop 0
	v_mul_f32_e32 v17, v17, v22
	v_mul_f32_e32 v22, v11, v11
	v_fmac_f32_e32 v22, v10, v10
	v_cvt_pk_bf16_f32 v10, v10, v11
	v_cvt_pk_bf16_f32 v11, v12, v13
	v_cvt_pk_bf16_f32 v12, v14, v15
	v_cvt_pk_bf16_f32 v13, v16, v17
	ds_bpermute_b32 v250, v255, v10
	ds_bpermute_b32 v251, v255, v11
	ds_bpermute_b32 v252, v255, v12
	ds_bpermute_b32 v253, v255, v13
	v_add_f32_e32 v22, v22, v23
	v_mul_f32_e32 v23, v15, v15
	v_mul_f32_e32 v10, 0x3d372713, v2
	v_fma_f32 v10, v2, v10, 1.0
	v_mul_f32_e32 v0, v0, v10
	v_mul_f32_e32 v0, 0xbfb8aa3b, v0
	v_exp_f32_e32 v0, v0
	v_mul_f32_e32 v10, 0x3d372713, v3
	v_fma_f32 v10, v3, v10, 1.0
	v_mul_f32_e32 v24, v17, v17
	v_add_f32_e32 v0, 1.0, v0
	v_rcp_f32_e32 v0, v0
	v_fmac_f32_e32 v23, v14, v14
	v_fmac_f32_e32 v24, v16, v16
	v_add_f32_e32 v23, v23, v24
	v_mul_f32_e32 v0, v2, v0
	v_mul_f32_e32 v2, 0x3fcc422a, v3
	v_mul_f32_e32 v2, v2, v10
	v_mul_f32_e32 v2, 0xbfb8aa3b, v2
	v_exp_f32_e32 v2, v2
	v_mul_f32_e32 v10, 0x3d372713, v4
	v_fma_f32 v10, v4, v10, 1.0
	v_add_f32_e32 v22, v22, v23
	v_add_f32_e32 v2, 1.0, v2
	v_rcp_f32_e32 v2, v2
	s_nop 0
	v_mul_f32_e32 v2, v3, v2
	v_mul_f32_e32 v3, 0x3fcc422a, v4
	v_mul_f32_e32 v3, v3, v10
	v_mul_f32_e32 v3, 0xbfb8aa3b, v3
	v_exp_f32_e32 v3, v3
	v_mul_f32_e32 v10, 0x3d372713, v5
	v_fma_f32 v10, v5, v10, 1.0
	v_add_f32_e32 v3, 1.0, v3
	v_rcp_f32_e32 v3, v3
	s_nop 0
	v_mul_f32_e32 v3, v4, v3
	v_mul_f32_e32 v4, 0x3fcc422a, v5
	v_mul_f32_e32 v4, v4, v10
	v_mul_f32_e32 v4, 0xbfb8aa3b, v4
	v_exp_f32_e32 v4, v4
	v_mul_f32_e32 v10, 0x3d372713, v6
	v_fma_f32 v10, v6, v10, 1.0
	v_add_f32_e32 v4, 1.0, v4
	v_rcp_f32_e32 v4, v4
	s_nop 0
	v_mul_f32_e32 v4, v5, v4
	v_mul_f32_e32 v5, 0x3fcc422a, v6
	v_mul_f32_e32 v5, v5, v10
	v_mul_f32_e32 v5, 0xbfb8aa3b, v5
	v_exp_f32_e32 v5, v5
	v_mul_f32_e32 v10, 0x3d372713, v7
	v_fma_f32 v10, v7, v10, 1.0
	v_add_f32_e32 v5, 1.0, v5
	v_rcp_f32_e32 v5, v5
	s_nop 0
	v_mul_f32_e32 v5, v6, v5
	v_mul_f32_e32 v6, 0x3fcc422a, v7
	v_mul_f32_e32 v6, v6, v10
	v_mul_f32_e32 v6, 0xbfb8aa3b, v6
	v_exp_f32_e32 v6, v6
	v_mul_f32_e32 v10, 0x3d372713, v8
	v_fma_f32 v10, v8, v10, 1.0
	v_add_f32_e32 v6, 1.0, v6
	v_rcp_f32_e32 v6, v6
	s_nop 0
	v_mul_f32_e32 v6, v7, v6
	v_mul_f32_e32 v7, 0x3fcc422a, v8
	v_mul_f32_e32 v7, v7, v10
	v_mul_f32_e32 v7, 0xbfb8aa3b, v7
	v_exp_f32_e32 v7, v7
	v_mul_f32_e32 v10, 0x3d372713, v9
	v_fma_f32 v10, v9, v10, 1.0
	v_add_f32_e32 v7, 1.0, v7
	v_rcp_f32_e32 v7, v7
	s_nop 0
	v_mul_f32_e32 v7, v8, v7
	v_mul_f32_e32 v8, 0x3fcc422a, v9
	v_mul_f32_e32 v8, v8, v10
	v_mul_f32_e32 v8, 0xbfb8aa3b, v8
	v_exp_f32_e32 v8, v8
	v_mul_f32_e32 v10, v4, v4
	v_fmac_f32_e32 v10, v3, v3
	v_add_f32_e32 v8, 1.0, v8
	v_rcp_f32_e32 v8, v8
	s_nop 0
	v_mul_f32_e32 v8, v9, v8
	v_mul_f32_e32 v9, v2, v2
	v_fmac_f32_e32 v9, v0, v0
	v_add_f32_e32 v9, v9, v10
	v_mul_f32_e32 v10, v6, v6
	v_mul_f32_e32 v11, v8, v8
	v_fmac_f32_e32 v10, v5, v5
	v_fmac_f32_e32 v11, v7, v7
	v_add_f32_e32 v10, v10, v11
	v_add_f32_e32 v9, v9, v10
	v_add_f32_e32 v9, v22, v9
	v_cvt_pk_bf16_f32 v2, v0, v2
	v_mov_b32_e32 v0, v9
	s_nop 1
	v_permlane16_swap_b32_e32 v9, v0
	v_add_f32_e32 v0, v9, v0
	v_cvt_pk_bf16_f32 v3, v3, v4
	v_cvt_pk_bf16_f32 v4, v5, v6
	v_cvt_pk_bf16_f32 v5, v7, v8
	ds_bpermute_b32 v2, v255, v2
	ds_bpermute_b32 v3, v255, v3
	ds_bpermute_b32 v4, v255, v4
	ds_bpermute_b32 v5, v255, v5
	v_lshl_add_u64 v[20:21], v[20:21], 0, v[208:209]
	s_waitcnt lgkmcnt(4)
	global_store_dwordx4 v[20:21], v[250:253], off
	s_waitcnt lgkmcnt(0)
	global_store_dwordx4 v[20:21], v[2:5], off offset:256
	s_nop 1
	v_mov_b32_e32 v2, v0
	s_nop 1
	v_permlane32_swap_b32_e32 v0, v2
	s_and_saveexec_b64 s[0:1], s[2:3]
	s_cbranch_execz .LBB0_189
	v_add_f32_e32 v0, v0, v2
	v_lshlrev_b64 v[2:3], 7, v[18:19]
	s_lshl_b32 s2, s12, 2
	v_lshl_add_u64 v[2:3], v[138:139], 0, v[2:3]
	s_mov_b32 s3, s40
	v_lshl_add_u64 v[2:3], s[2:3], 2, v[2:3]
	s_lshl_b32 s2, s28, 2
	v_lshl_add_u64 v[2:3], v[2:3], 0, s[2:3]
	global_store_dword v[2:3], v0, off offset:-128
